# attention loops: 32-bit saddr global loads and immediate-offset LDS writes (fewer 64-bit VALU address ops); MoBA max3 trees; MoBA K swizzle
# speedup vs baseline: 1.0060x; 1.0060x over previous
.LBB0_7:
	s_cmp_ge_i32 s28, s29
	s_cbranch_scc1 .LBB0_1029
	s_load_dwordx16 s[68:83], s[0:1], 0x0
	s_add_u32 s34, s0, 0x70
	s_addc_u32 s35, s1, 0
	v_lshrrev_b32_e32 v1, 20, v0
	v_lshrrev_b32_e32 v0, 10, v0
	s_waitcnt lgkmcnt(0)
	s_add_u32 s98, s70, 0x8000
	s_addc_u32 s99, s71, 0
	s_add_u32 s0, s70, 0x2000
	s_addc_u32 s1, s71, 0
	s_cmp_lg_u32 s30, 2
	s_cselect_b64 s[6:7], -1, 0
	v_writelane_b32 v253, s6, 10
	v_or_b32_e32 v0, v0, v1
	v_mov_b32_e32 v9, 0
	v_writelane_b32 v253, s7, 11
	v_mbcnt_lo_u32_b32 v1, -1, 0
	v_readlane_b32 s16, v253, 0
	v_readlane_b32 s22, v253, 6
	v_readlane_b32 s23, v253, 7
	s_add_u32 s6, s22, 0xc0200
	s_addc_u32 s7, s23, 0
	v_readlane_b32 s17, v253, 1
	v_readlane_b32 s18, v253, 2
	v_readlane_b32 s19, v253, 3
	v_readlane_b32 s20, v253, 4
	v_readlane_b32 s21, v253, 5
	v_writelane_b32 v253, s6, 12
	v_mov_b32_e32 v183, 0x358637bd
	v_mbcnt_hi_u32_b32 v184, -1, v1
	v_writelane_b32 v253, s7, 13
	s_add_u32 s6, s22, 0xc0400
	s_addc_u32 s7, s23, 0
	v_writelane_b32 v253, s6, 14
	v_mov_b32_e32 v185, 1
	v_mov_b32_e32 v186, 0x3d800000
	v_writelane_b32 v253, s7, 15
	s_add_u32 s6, s22, 0xc0500
	s_addc_u32 s7, s23, 0
	v_writelane_b32 v253, s6, 16
	v_mov_b64_e32 v[158:159], 0x300
	v_mov_b64_e32 v[160:161], 0x2ff
	v_writelane_b32 v253, s7, 17
	s_add_u32 s6, s22, 0xc0600
	s_addc_u32 s7, s23, 0
	v_writelane_b32 v253, s6, 18
	v_mov_b32_e32 v187, 0x3e0293ee
	v_mov_b64_e32 v[162:163], 0x100
	v_writelane_b32 v253, s7, 19
	s_add_u32 s6, s22, 0xc0700
	s_addc_u32 s7, s23, 0
	v_writelane_b32 v253, s6, 20
	v_mov_b64_e32 v[164:165], 0xff
	v_mov_b32_e32 v188, 0xff800000
	v_writelane_b32 v253, s7, 21
	s_add_u32 s6, s22, 0xc0800
	s_addc_u32 s7, s23, 0
	v_writelane_b32 v253, s6, 22
	v_mov_b64_e32 v[166:167], 0x580
	v_mov_b64_e32 v[168:169], 0x57f
	v_writelane_b32 v253, s7, 23
	s_add_u32 s6, s22, 0xc0900
	s_addc_u32 s7, s23, 0
	v_writelane_b32 v253, s6, 24
	v_mov_b32_e32 v224, v9
	v_mov_b32_e32 v225, v9
	v_writelane_b32 v253, s7, 25
	s_add_u32 s6, s22, 0xc0a00
	s_addc_u32 s7, s23, 0
	v_writelane_b32 v253, s6, 26
	s_movk_i32 s66, 0x2c00
	s_movk_i32 s67, 0x6000
	v_writelane_b32 v253, s7, 27
	s_add_u32 s6, s22, 0xc0b00
	s_addc_u32 s7, s23, 0
	v_writelane_b32 v253, s6, 28
	s_mov_b32 s64, 0xb000
	s_movk_i32 s65, 0x3000
	v_writelane_b32 v253, s7, 29
	s_add_u32 s6, s22, 0xc0c00
	s_addc_u32 s7, s23, 0
	v_writelane_b32 v253, s6, 30
	s_movk_i32 s96, 0x200
	s_movk_i32 s92, 0x220
	v_writelane_b32 v253, s7, 31
	s_add_u32 s6, s22, 0xc0d00
	s_addc_u32 s7, s23, 0
	v_writelane_b32 v253, s6, 32
	s_mov_b32 s93, 0x5040100
	s_movk_i32 s33, 0x100
	v_writelane_b32 v253, s7, 33
	s_add_u32 s6, s22, 0xc0e00
	s_addc_u32 s7, s23, 0
	v_writelane_b32 v253, s6, 34
	s_movk_i32 s84, 0x120
	s_flbit_i32_b32 s85, 0
	v_writelane_b32 v253, s7, 35
	s_add_u32 s6, s22, 0xc0f00
	s_addc_u32 s7, s23, 0
	v_writelane_b32 v253, s6, 36
	s_mov_b64 s[94:95], 0x80
	s_nop 0
	v_writelane_b32 v253, s7, 37
	s_add_u32 s6, s22, 0xc1000
	s_addc_u32 s7, s23, 0
	v_writelane_b32 v253, s6, 38
	s_nop 1
	v_writelane_b32 v253, s7, 39
	s_add_u32 s6, s22, 0xc1100
	s_addc_u32 s7, s23, 0
	v_writelane_b32 v253, s6, 40
	s_nop 1
	v_writelane_b32 v253, s7, 41
	s_add_u32 s6, s22, 0xc1200
	s_addc_u32 s7, s23, 0
	v_writelane_b32 v253, s6, 42
	s_nop 1
	v_writelane_b32 v253, s7, 43
	s_add_u32 s6, s22, 0xc1300
	s_addc_u32 s7, s23, 0
	v_writelane_b32 v253, s6, 44
	s_cmp_eq_u32 s12, 15
	s_nop 0
	v_writelane_b32 v253, s7, 45
	s_cselect_b64 s[6:7], -1, 0
	v_writelane_b32 v253, s6, 46
	s_cmp_eq_u32 s12, 14
	s_nop 0
	v_writelane_b32 v253, s7, 47
	s_cselect_b64 s[6:7], -1, 0
	v_writelane_b32 v253, s6, 48
	s_cmp_eq_u32 s12, 13
	s_nop 0
	v_writelane_b32 v253, s7, 49
	s_cselect_b64 s[6:7], -1, 0
	v_writelane_b32 v253, s6, 50
	s_cmp_eq_u32 s12, 12
	s_nop 0
	v_writelane_b32 v253, s7, 51
	s_cselect_b64 s[6:7], -1, 0
	v_writelane_b32 v253, s6, 52
	s_cmp_eq_u32 s12, 11
	s_nop 0
	v_writelane_b32 v253, s7, 53
	s_cselect_b64 s[6:7], -1, 0
	v_writelane_b32 v253, s6, 54
	s_cmp_eq_u32 s12, 10
	s_nop 0
	v_writelane_b32 v253, s7, 55
	s_cselect_b64 s[6:7], -1, 0
	v_writelane_b32 v253, s6, 56
	s_cmp_eq_u32 s12, 9
	s_nop 0
	v_writelane_b32 v253, s7, 57
	s_cselect_b64 s[6:7], -1, 0
	v_writelane_b32 v253, s6, 58
	s_cmp_eq_u32 s12, 8
	s_nop 0
	v_writelane_b32 v253, s7, 59
	s_cselect_b64 s[6:7], -1, 0
	v_writelane_b32 v253, s6, 60
	s_cmp_eq_u32 s12, 7
	s_nop 0
	v_writelane_b32 v253, s7, 61
	s_cselect_b64 s[6:7], -1, 0
	v_writelane_b32 v253, s6, 62
	s_cmp_eq_u32 s12, 6
	s_nop 0
	v_writelane_b32 v253, s7, 63
	s_cselect_b64 s[6:7], -1, 0
	v_writelane_b32 v254, s6, 0
	s_cmp_eq_u32 s12, 5
	s_nop 0
	v_writelane_b32 v254, s7, 1
	s_cselect_b64 s[6:7], -1, 0
	v_writelane_b32 v254, s6, 2
	s_cmp_eq_u32 s12, 4
	s_nop 0
	v_writelane_b32 v254, s7, 3
	s_cselect_b64 s[6:7], -1, 0
	v_writelane_b32 v254, s6, 4
	s_cmp_eq_u32 s12, 3
	s_nop 0
	v_writelane_b32 v254, s7, 5
	s_cselect_b64 s[6:7], -1, 0
	v_writelane_b32 v254, s6, 6
	s_cmp_eq_u32 s12, 2
	s_nop 0
	v_writelane_b32 v254, s7, 7
	s_cselect_b64 s[6:7], -1, 0
	v_writelane_b32 v254, s6, 8
	s_cmp_eq_u32 s12, 1
	s_nop 0
	v_writelane_b32 v254, s7, 9
	s_cselect_b64 s[6:7], -1, 0
	v_writelane_b32 v254, s6, 10
	s_cmp_eq_u32 s12, 0
	s_nop 0
	v_writelane_b32 v254, s7, 11
	s_cselect_b64 s[6:7], -1, 0
	s_lshl_b32 s3, s12, 8
	s_add_u32 s4, s4, s3
	v_writelane_b32 v254, s6, 12
	s_addc_u32 s3, s5, 0
	s_nop 0
	v_writelane_b32 v254, s7, 13
	s_add_u32 s6, s4, 0x1400
	s_addc_u32 s7, s3, 0
	v_writelane_b32 v254, s6, 14
	s_add_u32 s4, s4, 0x2400
	s_addc_u32 s5, s3, 0
	v_writelane_b32 v254, s7, 15
	v_writelane_b32 v254, s4, 16
	s_movk_i32 s3, 0x3ff
	v_and_or_b32 v0, v0, s3, v182
	v_writelane_b32 v254, s5, 17
	s_add_u32 s4, s22, 0xc3400
	s_addc_u32 s5, s23, 0
	v_writelane_b32 v254, s4, 18
	s_nop 1
	v_writelane_b32 v254, s5, 19
	s_add_u32 s4, s22, 0xc3500
	s_addc_u32 s5, s23, 0
	v_writelane_b32 v254, s4, 20
	s_add_u32 s3, s70, 0x78
	s_nop 0
	v_writelane_b32 v254, s5, 21
	v_writelane_b32 v254, s3, 22
	s_addc_u32 s3, s71, 0
	v_writelane_b32 v254, s3, 23
	s_add_u32 s3, s68, 0x1c00
	v_writelane_b32 v254, s3, 24
	s_addc_u32 s3, s69, 0
	v_writelane_b32 v254, s3, 25
	s_add_i32 s3, 0, 0x11800
	v_writelane_b32 v254, s3, 26
	s_add_i32 s4, 0, 0x23fc0
	v_writelane_b32 v254, s4, 27
	s_add_i32 s4, 0, 0x23fc4
	v_writelane_b32 v254, s4, 28
	v_cmp_eq_u32_e64 s[4:5], 0, v182
	s_add_i32 s97, 0, 0x10800
	s_mov_b32 s3, 0xff800000
	v_writelane_b32 v254, s4, 29
	s_mov_b32 s69, 0
	s_nop 0
	v_writelane_b32 v254, s5, 30
	v_cmp_eq_u32_e64 s[4:5], 0, v0
	s_nop 1
	v_writelane_b32 v254, s4, 31
	s_nop 1
	v_writelane_b32 v254, s5, 32
	v_writelane_b32 v254, s2, 33
	v_writelane_b32 v254, s34, 34
	s_nop 1
	v_writelane_b32 v254, s35, 35
	s_branch .LBB0_12

.LBB0_864:
	s_lshl_b32 s4, s49, 6
	s_nop 1
	s_xor_b32 s49, s4, 64
	s_mul_i32 s4, s49, 0x210
	v_lshrrev_b32_e32 v2, 5, v170
	v_and_b32_e32 v3, 31, v170
	v_and_b32_e32 v0, 15, v2
	v_xor_b32_e32 v0, v3, v0
	v_lshlrev_b32_e32 v0, 4, v0
	v_lshl_or_b32 v0, v2, 9, v0
	v_add_u32_e32 v0, s4, v0
	s_mulk_i32 s49, 0x220
	v_mul_u32_u24_e32 v1, 0x220, v2
	v_lshl_add_u32 v1, v3, 4, v1
	s_add_i32 s4, s49, 0x10800
	v_add_u32_e32 v1, s4, v1
	s_waitcnt vmcnt(7)
	ds_write_b128 v0, v[110:113]
	s_waitcnt vmcnt(6)
	ds_write_b128 v0, v[106:109] offset:8192
	s_waitcnt vmcnt(5)
	ds_write_b128 v0, v[118:121] offset:16384
	s_waitcnt vmcnt(4)
	ds_write_b128 v0, v[114:117] offset:24576
	s_waitcnt vmcnt(3)
	ds_write_b128 v1, v[126:129]
	s_waitcnt vmcnt(2)
	ds_write_b128 v1, v[122:125] offset:8704
	s_add_i32 s48, s48, 1
	s_add_i32 s45, s45, 64
	s_cmp_eq_u32 s17, s48
	v_subrev_u32_e32 v196, 64, v196
	s_waitcnt vmcnt(1)
	ds_write_b128 v1, v[134:137] offset:17408
	s_waitcnt vmcnt(0)
	ds_write_b128 v1, v[130:133] offset:26112
	s_waitcnt lgkmcnt(0)
	s_barrier
	s_cbranch_scc1 .LBB0_870
.LBB0_865:
	s_and_b32 s49, s48, 1
	v_lshrrev_b32_e32 v4, 5, v170
	v_and_b32_e32 v5, 31, v170
	v_lshlrev_b32_e32 v4, 14, v4
	v_lshl_or_b32 v4, v5, 4, v4
	s_lshl_b32 s4, s45, 14
	s_add_i32 s4, s4, 0x100000
	v_add_u32_e32 v0, s4, v4
	s_add_i32 s5, s4, 0x40000
	v_add_u32_e32 v1, s5, v4
	s_add_i32 s5, s4, 0x80000
	v_add_u32_e32 v2, s5, v4
	s_add_i32 s5, s4, 0xc0000
	v_add_u32_e32 v3, s5, v4
	global_load_dwordx4 v[110:113], v0, s[24:25]
	global_load_dwordx4 v[106:109], v1, s[24:25]
	global_load_dwordx4 v[118:121], v2, s[24:25]
	global_load_dwordx4 v[114:117], v3, s[24:25]
	global_load_dwordx4 v[126:129], v0, s[26:27]
	global_load_dwordx4 v[122:125], v1, s[26:27]
	global_load_dwordx4 v[134:137], v2, s[26:27]
	global_load_dwordx4 v[130:133], v3, s[26:27]
	s_cmp_gt_i32 s45, s16
	s_cbranch_scc1 .LBB0_864
	s_mul_i32 s4, s49, 0x8400
	v_add_u32_e32 v8, s4, v195
	v_xor_b32_e32 v246, 64, v8
	v_xor_b32_e32 v247, 0x80, v8
	v_xor_b32_e32 v248, 0xc0, v8
	ds_read_b128 v[0:3], v8
	ds_read_b128 v[4:7], v8 offset:8192
	ds_read_b128 v[174:177], v8 offset:16384
	ds_read_b128 v[198:201], v8 offset:24576
	ds_read_b128 v[202:205], v246
	ds_read_b128 v[206:209], v246 offset:8192
	ds_read_b128 v[210:213], v246 offset:16384
	ds_read_b128 v[214:217], v246 offset:24576
	ds_read_b128 v[218:221], v247
	ds_read_b128 v[226:229], v247 offset:8192
	ds_read_b128 v[230:233], v247 offset:16384
	ds_read_b128 v[234:237], v247 offset:24576
	ds_read_b128 v[238:241], v248
	ds_read_b128 v[242:245], v248 offset:8192
	s_add_i32 s4, s45, 63
	s_cmp_le_u32 s4, s9
	s_waitcnt lgkmcnt(13)
	v_mfma_f32_16x16x32_bf16 v[150:153], v[0:3], v[102:105], 0
	ds_read_b128 v[0:3], v248 offset:16384
	s_waitcnt lgkmcnt(13)
	v_mfma_f32_16x16x32_bf16 v[146:149], v[4:7], v[102:105], 0
	ds_read_b128 v[4:7], v248 offset:24576
	s_waitcnt lgkmcnt(13)
	v_mfma_f32_16x16x32_bf16 v[142:145], v[174:177], v[102:105], 0
	ds_read_b128 v[174:177], v8 offset:256
	s_waitcnt lgkmcnt(13)
	v_mfma_f32_16x16x32_bf16 v[138:141], v[198:201], v[102:105], 0
	ds_read_b128 v[198:201], v8 offset:8448
	s_waitcnt lgkmcnt(13)
	v_mfma_f32_16x16x32_bf16 v[150:153], v[202:205], v[98:101], v[150:153]
	ds_read_b128 v[202:205], v8 offset:16640
	s_waitcnt lgkmcnt(13)
	v_mfma_f32_16x16x32_bf16 v[146:149], v[206:209], v[98:101], v[146:149]
	ds_read_b128 v[206:209], v8 offset:24832
	s_waitcnt lgkmcnt(13)
	v_mfma_f32_16x16x32_bf16 v[142:145], v[210:213], v[98:101], v[142:145]
	ds_read_b128 v[210:213], v246 offset:256
	s_waitcnt lgkmcnt(13)
	v_mfma_f32_16x16x32_bf16 v[138:141], v[214:217], v[98:101], v[138:141]
	ds_read_b128 v[214:217], v246 offset:8448
	s_waitcnt lgkmcnt(13)
	v_mfma_f32_16x16x32_bf16 v[150:153], v[218:221], v[94:97], v[150:153]
	ds_read_b128 v[218:221], v246 offset:16640
	s_waitcnt lgkmcnt(13)
	v_mfma_f32_16x16x32_bf16 v[146:149], v[226:229], v[94:97], v[146:149]
	ds_read_b128 v[226:229], v246 offset:24832
	s_waitcnt lgkmcnt(13)
	v_mfma_f32_16x16x32_bf16 v[142:145], v[230:233], v[94:97], v[142:145]
	ds_read_b128 v[230:233], v247 offset:256
	s_waitcnt lgkmcnt(13)
	v_mfma_f32_16x16x32_bf16 v[138:141], v[234:237], v[94:97], v[138:141]
	ds_read_b128 v[234:237], v247 offset:8448
	s_waitcnt lgkmcnt(13)
	v_mfma_f32_16x16x32_bf16 v[150:153], v[238:241], v[90:93], v[150:153]
	ds_read_b128 v[238:241], v247 offset:16640
	s_waitcnt lgkmcnt(13)
	v_mfma_f32_16x16x32_bf16 v[146:149], v[242:245], v[90:93], v[146:149]
	ds_read_b128 v[242:245], v247 offset:24832
	s_waitcnt lgkmcnt(13)
	v_mfma_f32_16x16x32_bf16 v[142:145], v[0:3], v[90:93], v[142:145]
	ds_read_b128 v[0:3], v248 offset:256
	s_waitcnt lgkmcnt(13)
	v_mfma_f32_16x16x32_bf16 v[138:141], v[4:7], v[90:93], v[138:141]
	ds_read_b128 v[4:7], v248 offset:8448
	s_waitcnt lgkmcnt(13)
	v_mfma_f32_16x16x32_bf16 v[150:153], v[174:177], v[86:89], v[150:153]
	ds_read_b128 v[174:177], v248 offset:16640
	s_waitcnt lgkmcnt(13)
	v_mfma_f32_16x16x32_bf16 v[146:149], v[198:201], v[86:89], v[146:149]
	ds_read_b128 v[198:201], v248 offset:24832
	s_waitcnt lgkmcnt(13)
	v_mfma_f32_16x16x32_bf16 v[142:145], v[202:205], v[86:89], v[142:145]
	s_waitcnt lgkmcnt(12)
	v_mfma_f32_16x16x32_bf16 v[138:141], v[206:209], v[86:89], v[138:141]
	s_waitcnt lgkmcnt(11)
	v_mfma_f32_16x16x32_bf16 v[150:153], v[210:213], v[82:85], v[150:153]
	s_waitcnt lgkmcnt(10)
	v_mfma_f32_16x16x32_bf16 v[146:149], v[214:217], v[82:85], v[146:149]
	s_waitcnt lgkmcnt(9)
	v_mfma_f32_16x16x32_bf16 v[142:145], v[218:221], v[82:85], v[142:145]
	s_waitcnt lgkmcnt(8)
	v_mfma_f32_16x16x32_bf16 v[138:141], v[226:229], v[82:85], v[138:141]
	s_waitcnt lgkmcnt(7)
	v_mfma_f32_16x16x32_bf16 v[150:153], v[230:233], v[78:81], v[150:153]
	s_waitcnt lgkmcnt(6)
	v_mfma_f32_16x16x32_bf16 v[146:149], v[234:237], v[78:81], v[146:149]
	s_waitcnt lgkmcnt(5)
	v_mfma_f32_16x16x32_bf16 v[142:145], v[238:241], v[78:81], v[142:145]
	s_waitcnt lgkmcnt(4)
	v_mfma_f32_16x16x32_bf16 v[138:141], v[242:245], v[78:81], v[138:141]
	s_waitcnt lgkmcnt(3)
	v_mfma_f32_16x16x32_bf16 v[150:153], v[0:3], v[74:77], v[150:153]
	s_waitcnt lgkmcnt(2)
	v_mfma_f32_16x16x32_bf16 v[146:149], v[4:7], v[74:77], v[146:149]
	s_waitcnt lgkmcnt(1)
	v_mfma_f32_16x16x32_bf16 v[142:145], v[174:177], v[74:77], v[142:145]
	s_waitcnt lgkmcnt(0)
	v_mfma_f32_16x16x32_bf16 v[138:141], v[198:201], v[74:77], v[138:141]
	s_mov_b64 s[4:5], -1
	s_cbranch_scc0 .LBB0_868
	v_cvt_f32_i32_e32 v0, v196
	s_mov_b64 s[4:5], 0
	v_mul_f32_e32 v0, v178, v0
	v_exp_f32_e32 v8, v0
	s_nop 0
	v_mul_f32_e32 v0, s40, v8
	v_pk_mul_f32 v[2:3], s[40:41], v[0:1] op_sel_hi:[1,0]
	v_pk_mul_f32 v[0:1], s[42:43], v[0:1] op_sel_hi:[1,0]
	v_pk_mul_f32 v[2:3], v[2:3], v[150:151]
	v_pk_mul_f32 v[4:5], v[0:1], v[152:153]
	v_cvt_pk_bf16_f32 v0, v2, v3
	v_mul_f32_e32 v2, s44, v8
	v_cvt_pk_bf16_f32 v1, v4, v5
	v_pk_mul_f32 v[4:5], s[40:41], v[2:3] op_sel_hi:[1,0]
	v_pk_mul_f32 v[2:3], s[42:43], v[2:3] op_sel_hi:[1,0]
	v_pk_mul_f32 v[4:5], v[4:5], v[146:147]
	v_pk_mul_f32 v[6:7], v[2:3], v[148:149]
	v_cvt_pk_bf16_f32 v2, v4, v5
	v_mul_f32_e32 v4, s37, v8
	v_cvt_pk_bf16_f32 v3, v6, v7
	v_pk_mul_f32 v[6:7], s[40:41], v[4:5] op_sel_hi:[1,0]
	v_pk_mul_f32 v[4:5], s[42:43], v[4:5] op_sel_hi:[1,0]
	v_pk_mul_f32 v[6:7], v[6:7], v[142:143]
	v_pk_mul_f32 v[154:155], v[4:5], v[144:145]
	v_cvt_pk_bf16_f32 v4, v6, v7
	v_mul_f32_e32 v6, s36, v8
	v_cvt_pk_bf16_f32 v5, v154, v155
	v_pk_mul_f32 v[154:155], s[40:41], v[6:7] op_sel_hi:[1,0]
	v_pk_mul_f32 v[6:7], s[42:43], v[6:7] op_sel_hi:[1,0]
	v_pk_mul_f32 v[174:175], v[154:155], v[138:139]
	v_pk_mul_f32 v[176:177], v[6:7], v[140:141]

.LBB0_877:
	s_waitcnt lgkmcnt(0)
	v_max3_f32 v70, v11, v126, v127
	v_sub_f32_e32 v68, v113, v70
	v_exp_f32_e32 v68, v68
	v_sub_f32_e32 v69, v109, v70
	v_exp_f32_e32 v69, v69
	v_sub_f32_e32 v71, v73, v70
	v_exp_f32_e32 v71, v71
	v_sub_f32_e32 v72, v72, v70
	v_exp_f32_e32 v73, v72
	v_add_f32_e32 v72, 0, v68
	v_add_f32_e32 v72, v69, v72
	v_add_f32_e32 v72, v71, v72
	v_add_f32_e32 v76, v73, v72
	v_cvt_pk_bf16_f32 v72, v68, v69
	v_sub_f32_e32 v68, v112, v70
	v_exp_f32_e32 v68, v68
	v_sub_f32_e32 v69, v108, v70
	v_cvt_pk_bf16_f32 v73, v71, v73
	v_exp_f32_e32 v69, v69
	v_sub_f32_e32 v71, v75, v70
	v_exp_f32_e32 v71, v71
	v_sub_f32_e32 v74, v74, v70
	v_exp_f32_e32 v75, v74
	v_add_f32_e32 v74, v68, v76
	v_add_f32_e32 v74, v69, v74
	v_add_f32_e32 v74, v71, v74
	v_add_f32_e32 v76, v75, v74
	v_cvt_pk_bf16_f32 v74, v68, v69
	v_sub_f32_e32 v68, v111, v70
	v_exp_f32_e32 v68, v68
	v_sub_f32_e32 v69, v107, v70
	v_cvt_pk_bf16_f32 v75, v71, v75
	v_exp_f32_e32 v69, v69
	v_add_f32_e32 v71, v68, v76
	v_sub_f32_e32 v76, v104, v70
	v_exp_f32_e32 v76, v76
	v_sub_f32_e32 v8, v8, v70
	v_exp_f32_e32 v8, v8
	v_sub_f32_e32 v77, v114, v70
	v_exp_f32_e32 v77, v77
	v_add_f32_e32 v71, v69, v71
	v_add_f32_e32 v71, v76, v71
	v_add_f32_e32 v71, v8, v71
	v_cvt_pk_bf16_f32 v68, v68, v69
	v_cvt_pk_bf16_f32 v69, v76, v8
	v_add_f32_e32 v8, v77, v71
	v_sub_f32_e32 v71, v110, v70
	v_exp_f32_e32 v71, v71
	v_sub_f32_e32 v76, v106, v70
	v_exp_f32_e32 v76, v76
	v_sub_f32_e32 v11, v11, v70
	v_sub_f32_e32 v70, v105, v70
	v_exp_f32_e32 v78, v70
	v_add_f32_e32 v8, v71, v8
	v_add_f32_e32 v70, v76, v8
	v_exp_f32_e32 v8, v11
	v_add_f32_e32 v104, v78, v70
	v_max_f32_e32 v11, v89, v89
	v_cvt_pk_bf16_f32 v70, v77, v71
	v_fmac_f32_e32 v104, v10, v8
	v_max_f32_e32 v10, v88, v88
	v_cvt_pk_bf16_f32 v71, v76, v78
	v_max_f32_e32 v10, v11, v10
	v_max_f32_e32 v11, v90, v90
	v_max_f32_e32 v76, v92, v92
	v_max_f32_e32 v11, v76, v11
	v_max3_f32 v10, v94, v91, v10
	v_max3_f32 v11, v99, v95, v11
	v_max3_f32 v10, v10, s3, v11
	v_max_f32_e32 v11, v93, v93
	v_max_f32_e32 v76, v96, v96
	v_max_f32_e32 v11, v76, v11
	v_max_f32_e32 v76, v97, v97
	v_max_f32_e32 v77, v100, v100
	v_max_f32_e32 v76, v77, v76
	v_max3_f32 v11, v101, v98, v11
	v_max3_f32 v76, v103, v102, v76
	v_max3_f32 v10, v10, v11, v76
	ds_bpermute_b32 v11, v175, v10
	v_pk_mul_f32 v[66:67], v[66:67], v[8:9] op_sel_hi:[1,0]
	v_pk_mul_f32 v[64:65], v[64:65], v[8:9] op_sel_hi:[1,0]
	v_pk_mul_f32 v[62:63], v[62:63], v[8:9] op_sel_hi:[1,0]
	v_pk_mul_f32 v[60:61], v[60:61], v[8:9] op_sel_hi:[1,0]
	s_waitcnt lgkmcnt(0)
	v_max_f32_e32 v10, v10, v11
	ds_bpermute_b32 v11, v174, v10
	v_pk_mul_f32 v[58:59], v[58:59], v[8:9] op_sel_hi:[1,0]
	v_pk_mul_f32 v[56:57], v[56:57], v[8:9] op_sel_hi:[1,0]
	v_pk_mul_f32 v[54:55], v[54:55], v[8:9] op_sel_hi:[1,0]
	v_pk_mul_f32 v[52:53], v[52:53], v[8:9] op_sel_hi:[1,0]
	v_pk_mul_f32 v[50:51], v[50:51], v[8:9] op_sel_hi:[1,0]
	v_pk_mul_f32 v[48:49], v[48:49], v[8:9] op_sel_hi:[1,0]
	v_pk_mul_f32 v[46:47], v[46:47], v[8:9] op_sel_hi:[1,0]
	v_pk_mul_f32 v[44:45], v[44:45], v[8:9] op_sel_hi:[1,0]
	v_pk_mul_f32 v[42:43], v[42:43], v[8:9] op_sel_hi:[1,0]
	v_pk_mul_f32 v[40:41], v[40:41], v[8:9] op_sel_hi:[1,0]
	v_pk_mul_f32 v[38:39], v[38:39], v[8:9] op_sel_hi:[1,0]
	v_pk_mul_f32 v[36:37], v[36:37], v[8:9] op_sel_hi:[1,0]
	s_waitcnt lgkmcnt(0)
	v_max3_f32 v8, v181, v10, v11
	v_sub_f32_e32 v11, v94, v8
	v_exp_f32_e32 v11, v11
	v_sub_f32_e32 v76, v91, v8
	v_exp_f32_e32 v76, v76
	v_sub_f32_e32 v77, v89, v8
	v_exp_f32_e32 v77, v77
	v_sub_f32_e32 v78, v88, v8
	v_exp_f32_e32 v78, v78
	v_add_f32_e32 v79, 0, v11
	v_add_f32_e32 v79, v76, v79
	v_cvt_pk_bf16_f32 v80, v11, v76
	v_sub_f32_e32 v11, v99, v8
	v_sub_f32_e32 v76, v95, v8
	v_add_f32_e32 v79, v77, v79
	v_exp_f32_e32 v11, v11
	v_exp_f32_e32 v76, v76
	v_add_f32_e32 v79, v78, v79
	v_cvt_pk_bf16_f32 v81, v77, v78
	v_sub_f32_e32 v77, v92, v8
	v_sub_f32_e32 v78, v90, v8
	v_exp_f32_e32 v77, v77
	v_exp_f32_e32 v78, v78
	v_add_f32_e32 v79, v11, v79
	v_cvt_pk_bf16_f32 v82, v11, v76
	v_sub_f32_e32 v11, v101, v8
	v_add_f32_e32 v79, v76, v79
	v_exp_f32_e32 v11, v11
	v_sub_f32_e32 v76, v98, v8
	v_add_f32_e32 v79, v77, v79
	v_cvt_pk_bf16_f32 v83, v77, v78
	v_exp_f32_e32 v76, v76
	v_sub_f32_e32 v77, v96, v8
	v_add_f32_e32 v79, v78, v79
	v_exp_f32_e32 v77, v77
	v_sub_f32_e32 v78, v93, v8
	v_exp_f32_e32 v78, v78
	v_add_f32_e32 v79, v11, v79
	v_add_f32_e32 v79, v76, v79
	v_add_f32_e32 v79, v77, v79
	v_cvt_pk_bf16_f32 v76, v11, v76
	v_sub_f32_e32 v11, v103, v8
	v_add_f32_e32 v79, v78, v79
	v_cvt_pk_bf16_f32 v77, v77, v78
	v_exp_f32_e32 v11, v11
	v_sub_f32_e32 v78, v102, v8
	v_exp_f32_e32 v78, v78
	v_sub_f32_e32 v84, v100, v8
	v_sub_f32_e32 v10, v181, v8
	v_exp_f32_e32 v84, v84
	v_sub_f32_e32 v8, v97, v8
	v_exp_f32_e32 v8, v8
	v_add_f32_e32 v79, v11, v79
	v_add_f32_e32 v79, v78, v79
	s_mulk_i32 s6, 0x4800
	v_add_f32_e32 v79, v84, v79
	v_add_u32_e32 v106, s6, v176
	v_add_f32_e32 v105, v8, v79
	v_cvt_pk_bf16_f32 v79, v84, v8
	v_exp_f32_e32 v8, v10
	ds_read_b64_tr_b16 v[86:87], v106 offset:39424
	ds_read_b64_tr_b16 v[84:85], v106 offset:34816
	ds_read_b64_tr_b16 v[88:89], v106 offset:34848
	ds_read_b64_tr_b16 v[92:93], v106 offset:34880
	ds_read_b64_tr_b16 v[96:97], v106 offset:34912
	ds_read_b64_tr_b16 v[90:91], v106 offset:39456
	ds_read_b64_tr_b16 v[94:95], v106 offset:39488
	ds_read_b64_tr_b16 v[98:99], v106 offset:39520
	s_waitcnt lgkmcnt(6)
	v_mfma_f32_16x16x32_bf16 v[64:67], v[84:87], v[72:75], v[64:67]
	v_mul_f32_e64 v30, v30, v8
	v_mul_f32_e64 v31, v31, v8
	v_pk_mul_f32 v[28:29], v[28:29], v[8:9] op_sel_hi:[1,0]
	v_pk_mul_f32 v[22:23], v[22:23], v[8:9] op_sel_hi:[1,0]
	v_pk_mul_f32 v[20:21], v[20:21], v[8:9] op_sel_hi:[1,0]
	v_pk_mul_f32 v[6:7], v[6:7], v[8:9] op_sel_hi:[1,0]
	v_pk_mul_f32 v[4:5], v[4:5], v[8:9] op_sel_hi:[1,0]
	v_mfma_f32_16x16x32_bf16 v[28:31], v[84:87], v[80:83], v[28:31]
	v_mul_f32_e64 v14, v14, v8
	v_mul_f32_e64 v15, v15, v8
	v_pk_mul_f32 v[12:13], v[12:13], v[8:9] op_sel_hi:[1,0]
	v_cvt_pk_bf16_f32 v78, v11, v78
	s_waitcnt lgkmcnt(2)
	v_mfma_f32_16x16x32_bf16 v[60:63], v[88:91], v[72:75], v[60:63]
	v_mul_f32_e64 v34, v34, v8
	v_mul_f32_e64 v35, v35, v8
	v_pk_mul_f32 v[32:33], v[32:33], v[8:9] op_sel_hi:[1,0]
	v_pk_mul_f32 v[26:27], v[26:27], v[8:9] op_sel_hi:[1,0]
	v_mfma_f32_16x16x32_bf16 v[20:23], v[88:91], v[80:83], v[20:23]
	v_mul_f32_e64 v24, v24, v8
	v_mul_f32_e64 v25, v25, v8
	v_pk_mul_f32 v[18:19], v[18:19], v[8:9] op_sel_hi:[1,0]
	v_pk_mul_f32 v[16:17], v[16:17], v[8:9] op_sel_hi:[1,0]
	s_waitcnt lgkmcnt(1)
	v_mfma_f32_16x16x32_bf16 v[56:59], v[92:95], v[72:75], v[56:59]
	v_mul_f32_e64 v2, v2, v8
	v_mul_f32_e64 v3, v3, v8
	v_pk_mul_f32 v[0:1], v[0:1], v[8:9] op_sel_hi:[1,0]
	v_fmac_f32_e32 v105, v177, v8
	v_mfma_f32_16x16x32_bf16 v[4:7], v[92:95], v[80:83], v[4:7]
	ds_read_b64_tr_b16 v[84:85], v106 offset:34944
	ds_read_b64_tr_b16 v[88:89], v106 offset:34976
	ds_read_b64_tr_b16 v[92:93], v106 offset:35008
	ds_read_b64_tr_b16 v[100:101], v106 offset:35040
	ds_read_b64_tr_b16 v[86:87], v106 offset:39552
	ds_read_b64_tr_b16 v[90:91], v106 offset:39584
	ds_read_b64_tr_b16 v[94:95], v106 offset:39616
	ds_read_b64_tr_b16 v[102:103], v106 offset:39648
	s_waitcnt lgkmcnt(8)
	v_mfma_f32_16x16x32_bf16 v[52:55], v[96:99], v[72:75], v[52:55]
	v_mfma_f32_16x16x32_bf16 v[10:13], v[96:99], v[80:83], v[12:15]
	s_waitcnt lgkmcnt(3)
	v_mfma_f32_16x16x32_bf16 v[48:51], v[84:87], v[72:75], v[48:51]
	v_mfma_f32_16x16x32_bf16 v[32:35], v[84:87], v[80:83], v[32:35]
	s_waitcnt lgkmcnt(2)
	v_mfma_f32_16x16x32_bf16 v[44:47], v[88:91], v[72:75], v[44:47]
	v_mfma_f32_16x16x32_bf16 v[24:27], v[88:91], v[80:83], v[24:27]
	s_waitcnt lgkmcnt(1)
	v_mfma_f32_16x16x32_bf16 v[40:43], v[92:95], v[72:75], v[40:43]
	v_mfma_f32_16x16x32_bf16 v[16:19], v[92:95], v[80:83], v[16:19]
	ds_read_b64_tr_b16 v[84:85], v106 offset:44032
	ds_read_b64_tr_b16 v[88:89], v106 offset:44064
	ds_read_b64_tr_b16 v[92:93], v106 offset:44096
	ds_read_b64_tr_b16 v[96:97], v106 offset:44128
	ds_read_b64_tr_b16 v[86:87], v106 offset:48640
	ds_read_b64_tr_b16 v[90:91], v106 offset:48672
	ds_read_b64_tr_b16 v[94:95], v106 offset:48704
	ds_read_b64_tr_b16 v[98:99], v106 offset:48736
	s_waitcnt lgkmcnt(8)
	v_mfma_f32_16x16x32_bf16 v[36:39], v[100:103], v[72:75], v[36:39]
	v_mfma_f32_16x16x32_bf16 v[0:3], v[100:103], v[80:83], v[0:3]
	s_waitcnt lgkmcnt(3)
	v_mfma_f32_16x16x32_bf16 v[64:67], v[84:87], v[68:71], v[64:67]
	v_mfma_f32_16x16x32_bf16 v[28:31], v[84:87], v[76:79], v[28:31]
	s_waitcnt lgkmcnt(2)
	v_mfma_f32_16x16x32_bf16 v[60:63], v[88:91], v[68:71], v[60:63]
	v_mfma_f32_16x16x32_bf16 v[20:23], v[88:91], v[76:79], v[20:23]
	ds_read_b64_tr_b16 v[72:73], v106 offset:44160
	ds_read_b64_tr_b16 v[80:81], v106 offset:44192
	ds_read_b64_tr_b16 v[84:85], v106 offset:44224
	ds_read_b64_tr_b16 v[88:89], v106 offset:44256
	ds_read_b64_tr_b16 v[74:75], v106 offset:48768
	ds_read_b64_tr_b16 v[82:83], v106 offset:48800
	ds_read_b64_tr_b16 v[86:87], v106 offset:48832
	ds_read_b64_tr_b16 v[90:91], v106 offset:48864
	s_waitcnt lgkmcnt(9)
	v_mfma_f32_16x16x32_bf16 v[56:59], v[92:95], v[68:71], v[56:59]
	v_mfma_f32_16x16x32_bf16 v[4:7], v[92:95], v[76:79], v[4:7]
	s_waitcnt lgkmcnt(8)
	v_mfma_f32_16x16x32_bf16 v[52:55], v[96:99], v[68:71], v[52:55]
	v_mfma_f32_16x16x32_bf16 v[12:15], v[96:99], v[76:79], v[10:13]
	s_waitcnt lgkmcnt(3)
	v_mfma_f32_16x16x32_bf16 v[48:51], v[72:75], v[68:71], v[48:51]
	v_mfma_f32_16x16x32_bf16 v[32:35], v[72:75], v[76:79], v[32:35]
	s_waitcnt lgkmcnt(2)
	v_mfma_f32_16x16x32_bf16 v[44:47], v[80:83], v[68:71], v[44:47]
	v_mfma_f32_16x16x32_bf16 v[24:27], v[80:83], v[76:79], v[24:27]
	s_waitcnt lgkmcnt(1)
	v_mfma_f32_16x16x32_bf16 v[40:43], v[84:87], v[68:71], v[40:43]
	v_mfma_f32_16x16x32_bf16 v[16:19], v[84:87], v[76:79], v[16:19]
	s_waitcnt lgkmcnt(0)
	v_mfma_f32_16x16x32_bf16 v[36:39], v[88:91], v[68:71], v[36:39]
	v_mfma_f32_16x16x32_bf16 v[0:3], v[88:91], v[76:79], v[0:3]
	v_mov_b32_e32 v10, v104
	v_mov_b32_e32 v177, v105

.LBB0_892:
	global_load_dwordx4 v[24:27], v[6:7], off offset:16
	global_load_dwordx4 v[28:31], v[6:7], off
	global_load_dwordx4 v[32:35], v[6:7], off offset:-16
	global_load_dwordx4 v[36:39], v[6:7], off offset:-32
	v_add_u32_e32 v52, s5, v8
	v_add_u32_e32 v40, 0x11800, v52
	v_add_u32_e32 v44, 0x12000, v52
	ds_read_b128 v[40:43], v40
	ds_read_b128 v[44:47], v44
	v_add_u32_e32 v53, 0x11810, v52
	v_add_u32_e32 v54, 0x12010, v52
	s_addk_i32 s5, 0x80
	s_waitcnt lgkmcnt(1)
	v_mov_b32_e32 v51, v41
	s_waitcnt lgkmcnt(0)
	v_pk_mov_b32 v[40:41], v[44:45], v[40:41] op_sel:[1,0]
	v_mov_b32_e32 v50, v44
	v_lshl_add_u64 v[6:7], v[6:7], 0, 64
	s_cmpk_lg_i32 s5, 0x200
	s_waitcnt vmcnt(0)
	v_and_b32_e32 v49, 0xffff0000, v36
	v_lshlrev_b32_e32 v48, 16, v36
	v_pk_mul_f32 v[40:41], v[40:41], v[48:49] op_sel:[0,1] op_sel_hi:[1,0]
	v_mov_b32_e32 v36, v46
	v_pk_fma_f32 v[40:41], v[50:51], v[48:49], v[40:41]
	s_nop 0
	v_pk_add_f32 v[4:5], v[4:5], v[40:41]
	v_and_b32_e32 v41, 0xffff0000, v37
	v_lshlrev_b32_e32 v40, 16, v37
	v_mov_b32_e32 v37, v43
	v_pk_mov_b32 v[42:43], v[46:47], v[42:43] op_sel:[1,0]
	s_nop 0
	v_pk_mul_f32 v[42:43], v[42:43], v[40:41] op_sel:[0,1] op_sel_hi:[1,0]
	s_nop 0
	v_pk_fma_f32 v[36:37], v[36:37], v[40:41], v[42:43]
	ds_read_b128 v[40:43], v53
	ds_read_b128 v[44:47], v54
	v_pk_add_f32 v[4:5], v[4:5], v[36:37]
	v_and_b32_e32 v37, 0xffff0000, v38
	v_lshlrev_b32_e32 v36, 16, v38
	s_waitcnt lgkmcnt(1)
	v_mov_b32_e32 v49, v41
	s_waitcnt lgkmcnt(0)
	v_pk_mov_b32 v[40:41], v[44:45], v[40:41] op_sel:[1,0]
	v_mov_b32_e32 v48, v44
	v_pk_mul_f32 v[40:41], v[40:41], v[36:37] op_sel:[0,1] op_sel_hi:[1,0]
	v_mov_b32_e32 v38, v46
	v_pk_fma_f32 v[36:37], v[48:49], v[36:37], v[40:41]
	v_pk_mov_b32 v[40:41], v[46:47], v[42:43] op_sel:[1,0]
	v_pk_add_f32 v[4:5], v[4:5], v[36:37]
	v_and_b32_e32 v37, 0xffff0000, v39
	v_lshlrev_b32_e32 v36, 16, v39
	v_mov_b32_e32 v39, v43
	v_pk_mul_f32 v[40:41], v[40:41], v[36:37] op_sel:[0,1] op_sel_hi:[1,0]
	v_and_b32_e32 v45, 0xffff0000, v32
	v_pk_fma_f32 v[36:37], v[38:39], v[36:37], v[40:41]
	v_add_u32_e32 v40, 0x12020, v52
	v_pk_add_f32 v[4:5], v[4:5], v[36:37]
	v_add_u32_e32 v36, 0x11820, v52
	ds_read_b128 v[36:39], v36
	ds_read_b128 v[40:43], v40
	v_lshlrev_b32_e32 v44, 16, v32
	v_add_u32_e32 v48, 0x11830, v52
	v_add_u32_e32 v49, 0x12030, v52
	s_waitcnt lgkmcnt(1)
	v_mov_b32_e32 v47, v37
	s_waitcnt lgkmcnt(0)
	v_pk_mov_b32 v[36:37], v[40:41], v[36:37] op_sel:[1,0]
	v_mov_b32_e32 v46, v40
	v_pk_mul_f32 v[36:37], v[36:37], v[44:45] op_sel:[0,1] op_sel_hi:[1,0]
	v_mov_b32_e32 v32, v42
	v_pk_fma_f32 v[36:37], v[46:47], v[44:45], v[36:37]
	s_nop 0
	v_pk_add_f32 v[4:5], v[4:5], v[36:37]
	v_and_b32_e32 v37, 0xffff0000, v33
	v_lshlrev_b32_e32 v36, 16, v33
	v_mov_b32_e32 v33, v39
	v_pk_mov_b32 v[38:39], v[42:43], v[38:39] op_sel:[1,0]
	s_nop 0
	v_pk_mul_f32 v[38:39], v[38:39], v[36:37] op_sel:[0,1] op_sel_hi:[1,0]
	s_nop 0
	v_pk_fma_f32 v[32:33], v[32:33], v[36:37], v[38:39]
	ds_read_b128 v[36:39], v48
	ds_read_b128 v[40:43], v49
	v_pk_add_f32 v[4:5], v[4:5], v[32:33]
	v_and_b32_e32 v33, 0xffff0000, v34
	v_lshlrev_b32_e32 v32, 16, v34
	s_waitcnt lgkmcnt(1)
	v_mov_b32_e32 v45, v37
	s_waitcnt lgkmcnt(0)
	v_pk_mov_b32 v[36:37], v[40:41], v[36:37] op_sel:[1,0]
	v_mov_b32_e32 v44, v40
	v_pk_mul_f32 v[36:37], v[36:37], v[32:33] op_sel:[0,1] op_sel_hi:[1,0]
	v_mov_b32_e32 v34, v42
	v_pk_fma_f32 v[32:33], v[44:45], v[32:33], v[36:37]
	v_pk_mov_b32 v[36:37], v[42:43], v[38:39] op_sel:[1,0]
	v_pk_add_f32 v[4:5], v[4:5], v[32:33]
	v_and_b32_e32 v33, 0xffff0000, v35
	v_lshlrev_b32_e32 v32, 16, v35
	v_mov_b32_e32 v35, v39
	v_pk_mul_f32 v[36:37], v[36:37], v[32:33] op_sel:[0,1] op_sel_hi:[1,0]
	v_and_b32_e32 v41, 0xffff0000, v28
	v_pk_fma_f32 v[32:33], v[34:35], v[32:33], v[36:37]
	v_add_u32_e32 v36, 0x12040, v52
	v_pk_add_f32 v[4:5], v[4:5], v[32:33]
	v_add_u32_e32 v32, 0x11840, v52
	ds_read_b128 v[32:35], v32
	ds_read_b128 v[36:39], v36
	v_lshlrev_b32_e32 v40, 16, v28
	v_add_u32_e32 v44, 0x11850, v52
	v_add_u32_e32 v45, 0x12050, v52
	s_waitcnt lgkmcnt(1)
	v_mov_b32_e32 v43, v33
	s_waitcnt lgkmcnt(0)
	v_pk_mov_b32 v[32:33], v[36:37], v[32:33] op_sel:[1,0]
	v_mov_b32_e32 v42, v36
	v_pk_mul_f32 v[32:33], v[32:33], v[40:41] op_sel:[0,1] op_sel_hi:[1,0]
	v_mov_b32_e32 v28, v38
	v_pk_fma_f32 v[32:33], v[42:43], v[40:41], v[32:33]
	s_nop 0
	v_pk_add_f32 v[4:5], v[4:5], v[32:33]
	v_and_b32_e32 v33, 0xffff0000, v29
	v_lshlrev_b32_e32 v32, 16, v29
	v_mov_b32_e32 v29, v35
	v_pk_mov_b32 v[34:35], v[38:39], v[34:35] op_sel:[1,0]
	s_nop 0
	v_pk_mul_f32 v[34:35], v[34:35], v[32:33] op_sel:[0,1] op_sel_hi:[1,0]
	s_nop 0
	v_pk_fma_f32 v[28:29], v[28:29], v[32:33], v[34:35]
	ds_read_b128 v[32:35], v44
	ds_read_b128 v[36:39], v45
	v_pk_add_f32 v[4:5], v[4:5], v[28:29]
	v_and_b32_e32 v29, 0xffff0000, v30
	v_lshlrev_b32_e32 v28, 16, v30
	s_waitcnt lgkmcnt(1)
	v_mov_b32_e32 v41, v33
	s_waitcnt lgkmcnt(0)
	v_pk_mov_b32 v[32:33], v[36:37], v[32:33] op_sel:[1,0]
	v_mov_b32_e32 v40, v36
	v_pk_mul_f32 v[32:33], v[32:33], v[28:29] op_sel:[0,1] op_sel_hi:[1,0]
	v_mov_b32_e32 v30, v38
	v_pk_fma_f32 v[28:29], v[40:41], v[28:29], v[32:33]
	v_pk_mov_b32 v[32:33], v[38:39], v[34:35] op_sel:[1,0]
	v_pk_add_f32 v[4:5], v[4:5], v[28:29]
	v_and_b32_e32 v29, 0xffff0000, v31
	v_lshlrev_b32_e32 v28, 16, v31
	v_mov_b32_e32 v31, v35
	v_pk_mul_f32 v[32:33], v[32:33], v[28:29] op_sel:[0,1] op_sel_hi:[1,0]
	v_and_b32_e32 v37, 0xffff0000, v24
	v_pk_fma_f32 v[28:29], v[30:31], v[28:29], v[32:33]
	v_add_u32_e32 v32, 0x12060, v52
	v_pk_add_f32 v[4:5], v[4:5], v[28:29]
	v_add_u32_e32 v28, 0x11860, v52
	ds_read_b128 v[28:31], v28
	ds_read_b128 v[32:35], v32
	v_lshlrev_b32_e32 v36, 16, v24
	v_add_u32_e32 v40, 0x11870, v52
	v_add_u32_e32 v41, 0x12070, v52
	s_waitcnt lgkmcnt(1)
	v_mov_b32_e32 v39, v29
	s_waitcnt lgkmcnt(0)
	v_pk_mov_b32 v[28:29], v[32:33], v[28:29] op_sel:[1,0]
	v_mov_b32_e32 v38, v32
	v_pk_mul_f32 v[28:29], v[28:29], v[36:37] op_sel:[0,1] op_sel_hi:[1,0]
	v_mov_b32_e32 v24, v34
	v_pk_fma_f32 v[28:29], v[38:39], v[36:37], v[28:29]
	s_nop 0
	v_pk_add_f32 v[4:5], v[4:5], v[28:29]
	v_and_b32_e32 v29, 0xffff0000, v25
	v_lshlrev_b32_e32 v28, 16, v25
	v_mov_b32_e32 v25, v31
	v_pk_mov_b32 v[30:31], v[34:35], v[30:31] op_sel:[1,0]
	s_nop 0
	v_pk_mul_f32 v[30:31], v[30:31], v[28:29] op_sel:[0,1] op_sel_hi:[1,0]
	s_nop 0
	v_pk_fma_f32 v[24:25], v[24:25], v[28:29], v[30:31]
	ds_read_b128 v[28:31], v40
	ds_read_b128 v[32:35], v41
	v_pk_add_f32 v[4:5], v[4:5], v[24:25]
	v_and_b32_e32 v25, 0xffff0000, v26
	v_lshlrev_b32_e32 v24, 16, v26
	s_waitcnt lgkmcnt(1)
	v_mov_b32_e32 v37, v29
	s_waitcnt lgkmcnt(0)
	v_pk_mov_b32 v[28:29], v[32:33], v[28:29] op_sel:[1,0]
	v_mov_b32_e32 v36, v32
	v_pk_mul_f32 v[28:29], v[28:29], v[24:25] op_sel:[0,1] op_sel_hi:[1,0]
	v_mov_b32_e32 v26, v34
	v_pk_fma_f32 v[24:25], v[36:37], v[24:25], v[28:29]
	v_pk_mov_b32 v[28:29], v[34:35], v[30:31] op_sel:[1,0]
	v_pk_add_f32 v[4:5], v[4:5], v[24:25]
	v_and_b32_e32 v25, 0xffff0000, v27
	v_lshlrev_b32_e32 v24, 16, v27
	v_mov_b32_e32 v27, v31
	v_pk_mul_f32 v[28:29], v[28:29], v[24:25] op_sel:[0,1] op_sel_hi:[1,0]
	s_nop 0
	v_pk_fma_f32 v[24:25], v[26:27], v[24:25], v[28:29]
	s_nop 0
	v_pk_add_f32 v[4:5], v[4:5], v[24:25]
	s_cbranch_scc1 .LBB0_892
	s_cmp_eq_u32 s52, 0
	s_cselect_b64 s[42:43], -1, 0
	s_cmp_gt_u32 s52, 1
	s_cselect_b64 s[46:47], -1, 0
	s_cmp_gt_u32 s52, 2
	v_cndmask_b32_e64 v6, v23, v188, s[42:43]
	v_cndmask_b32_e64 v7, v188, v22, s[46:47]
	s_cselect_b64 vcc, -1, 0
	v_cndmask_b32_e32 v8, v188, v21, vcc
	s_cmp_gt_u32 s52, 3
	v_cmp_gt_f32_e64 s[50:51], v7, v6
	s_cselect_b64 s[38:39], -1, 0
	s_cmp_gt_u32 s52, 4
	v_cndmask_b32_e64 v21, 0, 1, s[50:51]
	v_cmp_gt_f32_e64 s[50:51], v8, v6
	v_cndmask_b32_e64 v20, v188, v20, s[38:39]
	s_cselect_b64 s[40:41], -1, 0
	v_addc_co_u32_e64 v21, s[50:51], 0, v21, s[50:51]
	v_cndmask_b32_e64 v19, v188, v19, s[40:41]
	s_cmp_gt_u32 s52, 5
	v_cmp_gt_f32_e64 s[50:51], v20, v6
	s_cselect_b64 s[44:45], -1, 0
	s_cmp_eq_u32 s52, 7
	v_cndmask_b32_e64 v22, 0, 1, s[50:51]
	v_cmp_gt_f32_e64 s[50:51], v19, v6
	v_cndmask_b32_e64 v18, v188, v18, s[44:45]
	s_cselect_b64 s[48:49], -1, 0
	v_addc_co_u32_e64 v21, s[50:51], v21, v22, s[50:51]
	v_cndmask_b32_e64 v17, v188, v17, s[48:49]
	v_cmp_gt_f32_e64 s[50:51], v18, v6
	s_lshl_b32 s5, -1, s52
	v_lshlrev_b32_e32 v191, 2, v12
	v_cndmask_b32_e64 v22, 0, 1, s[50:51]
	v_cmp_gt_f32_e64 s[50:51], v17, v6
	s_lshl_b32 s17, s52, 2
	s_mov_b32 s85, 0
	v_addc_co_u32_e64 v21, s[50:51], v21, v22, s[50:51]
	v_cmp_gt_u32_e64 s[50:51], 3, v21
	s_or_b32 s16, s4, 31
	v_add_u32_e32 v179, 14, v149
	v_cndmask_b32_e64 v21, 0, 1, s[50:51]
	v_cmp_ge_f32_e64 s[50:51], v6, v7
	v_add_u32_e32 v178, 13, v149
	v_mov_b32_e32 v177, 0
	v_cndmask_b32_e64 v22, 0, 1, s[50:51]
	v_cmp_gt_f32_e64 s[50:51], v8, v7
	v_mov_b32_e32 v181, 0xf149f2ca
	s_nop 0
	v_addc_co_u32_e64 v22, s[50:51], 0, v22, s[50:51]
	v_cmp_gt_f32_e64 s[50:51], v20, v7
	s_nop 1
	v_cndmask_b32_e64 v23, 0, 1, s[50:51]
	v_cmp_gt_f32_e64 s[50:51], v19, v7
	s_nop 1
	v_addc_co_u32_e64 v22, s[50:51], v22, v23, s[50:51]
	v_cmp_gt_f32_e64 s[50:51], v18, v7
	s_nop 1
	v_cndmask_b32_e64 v23, 0, 1, s[50:51]
	v_cmp_gt_f32_e64 s[50:51], v17, v7
	s_nop 1
	v_addc_co_u32_e64 v22, s[50:51], v22, v23, s[50:51]
	v_cmp_lt_u32_e64 s[50:51], 2, v22
	s_nop 1
	v_cndmask_b32_e64 v22, 2, 0, s[50:51]
	v_cmp_ge_f32_e64 s[50:51], v7, v8
	v_or_b32_e32 v21, v22, v21
	s_nop 0
	v_cndmask_b32_e64 v22, 0, 1, s[50:51]
	v_cmp_ge_f32_e64 s[50:51], v6, v8
	s_nop 1
	v_addc_co_u32_e64 v22, s[50:51], 0, v22, s[50:51]
	v_cmp_gt_f32_e64 s[50:51], v20, v8
	s_nop 1
	v_cndmask_b32_e64 v23, 0, 1, s[50:51]
	v_cmp_gt_f32_e64 s[50:51], v19, v8
	s_nop 1
	v_addc_co_u32_e64 v22, s[50:51], v22, v23, s[50:51]
	v_cmp_gt_f32_e64 s[50:51], v18, v8
	s_nop 1
	v_cndmask_b32_e64 v23, 0, 1, s[50:51]
	v_cmp_gt_f32_e64 s[50:51], v17, v8
	s_nop 1
	v_addc_co_u32_e64 v22, s[50:51], v22, v23, s[50:51]
	v_cmp_gt_u32_e64 s[50:51], 3, v22
	s_nop 1
	v_cndmask_b32_e64 v22, 0, 4, s[50:51]
	v_cmp_ge_f32_e64 s[50:51], v7, v20
	s_nop 1
	v_cndmask_b32_e64 v23, 0, 1, s[50:51]
	v_cmp_ge_f32_e64 s[50:51], v6, v20
	s_nop 1
	v_addc_co_u32_e64 v23, s[50:51], 0, v23, s[50:51]
	v_cmp_ge_f32_e64 s[50:51], v8, v20
	s_nop 1
	v_cndmask_b32_e64 v24, 0, 1, s[50:51]
	v_cmp_gt_f32_e64 s[50:51], v19, v20
	s_nop 1
	v_addc_co_u32_e64 v23, s[50:51], v23, v24, s[50:51]
	v_cmp_gt_f32_e64 s[50:51], v18, v20
	s_nop 1
	v_cndmask_b32_e64 v24, 0, 1, s[50:51]
	v_cmp_gt_f32_e64 s[50:51], v17, v20
	s_nop 1
	v_addc_co_u32_e64 v23, s[50:51], v23, v24, s[50:51]
	v_cmp_gt_u32_e64 s[50:51], 3, v23
	s_nop 1
	v_cndmask_b32_e64 v23, 0, 8, s[50:51]
	v_cmp_ge_f32_e64 s[50:51], v7, v19
	v_or3_b32 v21, v21, v22, v23
	s_nop 0
	v_cndmask_b32_e64 v22, 0, 1, s[50:51]
	v_cmp_ge_f32_e64 s[50:51], v6, v19
	s_nop 1
	v_addc_co_u32_e64 v22, s[50:51], 0, v22, s[50:51]
	v_cmp_ge_f32_e64 s[50:51], v8, v19
	s_nop 1
	v_cndmask_b32_e64 v23, 0, 1, s[50:51]
	v_cmp_ge_f32_e64 s[50:51], v20, v19
	s_nop 1
	v_addc_co_u32_e64 v22, s[50:51], v22, v23, s[50:51]
	v_cmp_gt_f32_e64 s[50:51], v18, v19
	s_nop 1
	v_cndmask_b32_e64 v23, 0, 1, s[50:51]
	v_cmp_gt_f32_e64 s[50:51], v17, v19
	s_nop 1
	v_addc_co_u32_e64 v22, s[50:51], v22, v23, s[50:51]
	v_cmp_gt_u32_e64 s[50:51], 3, v22
	s_nop 1
	v_cndmask_b32_e64 v22, 0, 16, s[50:51]
	v_cmp_ge_f32_e64 s[50:51], v7, v18
	s_nop 1
	v_cndmask_b32_e64 v23, 0, 1, s[50:51]
	v_cmp_ge_f32_e64 s[50:51], v6, v18
	s_nop 1
	v_addc_co_u32_e64 v23, s[50:51], 0, v23, s[50:51]
	v_cmp_ge_f32_e64 s[50:51], v8, v18
	s_nop 1
	v_cndmask_b32_e64 v24, 0, 1, s[50:51]
	v_cmp_ge_f32_e64 s[50:51], v20, v18
	s_nop 1
	v_addc_co_u32_e64 v23, s[50:51], v23, v24, s[50:51]
	v_cmp_ge_f32_e64 s[50:51], v19, v18
	s_nop 1
	v_cndmask_b32_e64 v24, 0, 1, s[50:51]
	v_cmp_gt_f32_e64 s[50:51], v17, v18
	s_nop 1
	v_addc_co_u32_e64 v23, s[50:51], v23, v24, s[50:51]
	v_cmp_gt_u32_e64 s[50:51], 3, v23
	s_nop 1
	v_cndmask_b32_e64 v23, 0, 32, s[50:51]
	v_cmp_ge_f32_e64 s[50:51], v7, v17
	v_or3_b32 v21, v21, v22, v23
	s_nop 0
	v_cndmask_b32_e64 v7, 0, 1, s[50:51]
	v_cmp_ge_f32_e64 s[50:51], v6, v17
	s_nop 1
	v_addc_co_u32_e64 v6, s[50:51], 0, v7, s[50:51]
	v_cmp_ge_f32_e64 s[50:51], v8, v17
	ds_bpermute_b32 v8, v14, v5
	s_waitcnt lgkmcnt(0)
	v_cndmask_b32_e64 v23, v188, v8, s[46:47]
	v_cndmask_b32_e64 v7, 0, 1, s[50:51]
	v_cmp_ge_f32_e64 s[50:51], v20, v17
	ds_bpermute_b32 v8, v14, v4
	s_waitcnt lgkmcnt(0)
	v_cndmask_b32_e64 v27, v188, v8, s[44:45]
	v_addc_co_u32_e64 v6, s[50:51], v6, v7, s[50:51]
	v_cmp_ge_f32_e64 s[50:51], v19, v17
	v_lshlrev_b32_e32 v8, 4, v12
	s_nop 0
	v_cndmask_b32_e64 v7, 0, 1, s[50:51]
	v_cmp_ge_f32_e64 s[50:51], v18, v17
	s_nop 1
	v_addc_co_u32_e64 v6, s[50:51], v6, v7, s[50:51]
	ds_bpermute_b32 v7, v13, v5
	v_cmp_gt_u32_e64 s[50:51], 3, v6
	s_waitcnt lgkmcnt(0)
	v_cndmask_b32_e64 v22, v7, v188, s[42:43]
	v_cndmask_b32_e64 v6, 0, 64, s[50:51]
	v_or_b32_e32 v24, v21, v6
	v_bitop3_b32 v190, v21, s5, v6 bitop3:0x32
	ds_bpermute_b32 v6, v15, v5
	ds_bpermute_b32 v7, v13, v4
	ds_bpermute_b32 v4, v15, v4
	ds_bpermute_b32 v5, v16, v5
	s_waitcnt lgkmcnt(3)
	v_cndmask_b32_e32 v13, v188, v6, vcc
	v_cmp_gt_f32_e32 vcc, v23, v22
	s_waitcnt lgkmcnt(1)
	v_cndmask_b32_e64 v28, v188, v4, s[48:49]
	s_waitcnt lgkmcnt(0)
	v_cndmask_b32_e64 v25, v188, v5, s[38:39]
	v_cndmask_b32_e64 v4, 0, 1, vcc
	v_cmp_gt_f32_e32 vcc, v13, v22
	v_cndmask_b32_e64 v26, v188, v7, s[40:41]
	s_nop 0
	v_addc_co_u32_e32 v4, vcc, 0, v4, vcc
	v_cmp_gt_f32_e32 vcc, v25, v22
	s_nop 1
	v_cndmask_b32_e64 v5, 0, 1, vcc
	v_cmp_gt_f32_e32 vcc, v26, v22
	s_nop 1
	v_addc_co_u32_e32 v4, vcc, v4, v5, vcc
	v_cmp_gt_f32_e32 vcc, v27, v22
	s_nop 1
	v_cndmask_b32_e64 v5, 0, 1, vcc
	v_cmp_gt_f32_e32 vcc, v28, v22
	s_nop 1
	v_addc_co_u32_e32 v4, vcc, v4, v5, vcc
	v_cmp_gt_u32_e32 vcc, 3, v4
	s_nop 1
	v_cndmask_b32_e64 v4, 0, 1, vcc
	v_cmp_ge_f32_e32 vcc, v22, v23
	s_nop 1
	v_cndmask_b32_e64 v5, 0, 1, vcc
	v_cmp_gt_f32_e32 vcc, v13, v23
	s_nop 1
	v_addc_co_u32_e32 v5, vcc, 0, v5, vcc
	v_cmp_gt_f32_e32 vcc, v25, v23
	s_nop 1
	v_cndmask_b32_e64 v6, 0, 1, vcc
	v_cmp_gt_f32_e32 vcc, v26, v23
	s_nop 1
	v_addc_co_u32_e32 v5, vcc, v5, v6, vcc
	v_cmp_gt_f32_e32 vcc, v27, v23
	s_nop 1
	v_cndmask_b32_e64 v6, 0, 1, vcc
	v_cmp_gt_f32_e32 vcc, v28, v23
	s_nop 1
	v_addc_co_u32_e32 v5, vcc, v5, v6, vcc
	v_cmp_lt_u32_e32 vcc, 2, v5
	v_mov_b32_e32 v6, v170
	s_nop 0
	v_cndmask_b32_e64 v5, 2, 0, vcc
	v_cmp_ge_f32_e32 vcc, v23, v13
	v_or_b32_e32 v29, v5, v4
	s_nop 0
	v_cndmask_b32_e64 v4, 0, 1, vcc
	v_cmp_ge_f32_e32 vcc, v22, v13
	s_nop 1
	v_addc_co_u32_e32 v4, vcc, 0, v4, vcc
	v_cmp_gt_f32_e32 vcc, v25, v13
	s_nop 1
	v_cndmask_b32_e64 v5, 0, 1, vcc
	v_cmp_gt_f32_e32 vcc, v26, v13
	s_nop 1
	v_addc_co_u32_e32 v4, vcc, v4, v5, vcc
	v_cmp_gt_f32_e32 vcc, v27, v13
	s_nop 1
	v_cndmask_b32_e64 v5, 0, 1, vcc
	v_cmp_gt_f32_e32 vcc, v28, v13
	s_nop 1
	v_addc_co_u32_e32 v4, vcc, v4, v5, vcc
	v_cmp_gt_u32_e32 vcc, 3, v4
	s_nop 1
	v_cndmask_b32_e64 v30, 0, 4, vcc
	v_cmp_ge_f32_e32 vcc, v23, v25
	s_nop 1
	v_cndmask_b32_e64 v4, 0, 1, vcc
	v_cmp_ge_f32_e32 vcc, v22, v25
	s_nop 1
	v_addc_co_u32_e32 v4, vcc, 0, v4, vcc
	v_cmp_ge_f32_e32 vcc, v13, v25
	s_nop 1
	v_cndmask_b32_e64 v5, 0, 1, vcc
	v_cmp_gt_f32_e32 vcc, v26, v25
	s_nop 1
	v_addc_co_u32_e32 v31, vcc, v4, v5, vcc
	v_lshl_add_u64 v[4:5], s[22:23], 0, v[8:9]
	v_lshl_add_u64 v[0:1], v[4:5], 0, v[0:1]
	global_load_dwordx4 v[92:95], v[0:1], off
	global_load_dwordx4 v[84:87], v[0:1], off offset:64
	global_load_dwordx4 v[76:79], v[0:1], off offset:128
	global_load_dwordx4 v[68:71], v[0:1], off offset:192
	v_lshl_add_u64 v[0:1], v[4:5], 0, v[2:3]
	global_load_dwordx4 v[96:99], v[0:1], off
	global_load_dwordx4 v[88:91], v[0:1], off offset:64
	global_load_dwordx4 v[80:83], v[0:1], off offset:128
	global_load_dwordx4 v[72:75], v[0:1], off offset:192
	v_cmp_gt_f32_e32 vcc, v27, v25
	v_lshlrev_b32_e32 v0, 4, v6
	v_and_b32_e32 v8, 0xf0, v0
	v_lshrrev_b32_e32 v0, 4, v6
	v_lshl_add_u64 v[4:5], s[24:25], 0, v[8:9]
	v_add_u32_e32 v14, s9, v0
	v_mad_u64_u32 v[0:1], s[6:7], v14, s65, v[4:5]
	v_add_u32_e32 v6, 0x200, v6
	global_load_dwordx4 v[0:3], v[0:1], off
	v_lshrrev_b32_e32 v6, 4, v6
	v_add_u32_e32 v20, s9, v6
	v_mad_u64_u32 v[4:5], s[6:7], v20, s65, v[4:5]
	v_lshl_add_u64 v[18:19], s[26:27], 0, v[8:9]
	global_load_dwordx4 v[4:7], v[4:5], off
	v_mad_u64_u32 v[14:15], s[6:7], v14, s65, v[18:19]
	global_load_dwordx4 v[14:17], v[14:15], off
	v_mad_u64_u32 v[18:19], s[6:7], v20, s65, v[18:19]
	global_load_dwordx4 v[18:21], v[18:19], off
	v_cndmask_b32_e64 v32, 0, 1, vcc
	v_cmp_gt_f32_e32 vcc, v28, v25
	s_nop 1
	v_addc_co_u32_e32 v8, vcc, v31, v32, vcc
	v_cmp_gt_u32_e32 vcc, 3, v8
	s_nop 1
	v_cndmask_b32_e64 v8, 0, 8, vcc
	v_cmp_ge_f32_e32 vcc, v23, v26
	v_or3_b32 v8, v29, v30, v8
	s_nop 0
	v_cndmask_b32_e64 v29, 0, 1, vcc
	v_cmp_ge_f32_e32 vcc, v22, v26
	s_nop 1
	v_addc_co_u32_e32 v29, vcc, 0, v29, vcc
	v_cmp_ge_f32_e32 vcc, v13, v26
	s_nop 1
	v_cndmask_b32_e64 v30, 0, 1, vcc
	v_cmp_ge_f32_e32 vcc, v25, v26
	s_nop 1
	v_addc_co_u32_e32 v29, vcc, v29, v30, vcc
	v_cmp_gt_f32_e32 vcc, v27, v26
	s_nop 1
	v_cndmask_b32_e64 v30, 0, 1, vcc
	v_cmp_gt_f32_e32 vcc, v28, v26
	s_nop 1
	v_addc_co_u32_e32 v29, vcc, v29, v30, vcc
	v_cmp_gt_u32_e32 vcc, 3, v29
	s_nop 1
	v_cndmask_b32_e64 v29, 0, 16, vcc
	v_cmp_ge_f32_e32 vcc, v23, v27
	s_nop 1
	v_cndmask_b32_e64 v30, 0, 1, vcc
	v_cmp_ge_f32_e32 vcc, v22, v27
	s_nop 1
	v_addc_co_u32_e32 v30, vcc, 0, v30, vcc
	v_cmp_ge_f32_e32 vcc, v13, v27
	s_nop 1
	v_cndmask_b32_e64 v31, 0, 1, vcc
	v_cmp_ge_f32_e32 vcc, v25, v27
	s_nop 1
	v_addc_co_u32_e32 v30, vcc, v30, v31, vcc
	v_cmp_ge_f32_e32 vcc, v26, v27
	s_nop 1
	v_cndmask_b32_e64 v31, 0, 1, vcc
	v_cmp_gt_f32_e32 vcc, v28, v27
	s_nop 1
	v_addc_co_u32_e32 v30, vcc, v30, v31, vcc
	v_cmp_gt_u32_e32 vcc, 3, v30
	s_nop 1
	v_cndmask_b32_e64 v30, 0, 32, vcc
	v_cmp_ge_f32_e32 vcc, v23, v28
	v_or3_b32 v8, v8, v29, v30
	s_nop 0
	v_cndmask_b32_e64 v23, 0, 1, vcc
	v_cmp_ge_f32_e32 vcc, v22, v28
	s_nop 1
	v_addc_co_u32_e32 v22, vcc, 0, v23, vcc
	v_cmp_ge_f32_e32 vcc, v13, v28
	s_nop 1
	v_cndmask_b32_e64 v13, 0, 1, vcc
	v_cmp_ge_f32_e32 vcc, v25, v28
	s_nop 1
	v_addc_co_u32_e32 v13, vcc, v22, v13, vcc
	v_cmp_ge_f32_e32 vcc, v26, v28
	s_nop 1
	v_cndmask_b32_e64 v22, 0, 1, vcc
	v_cmp_ge_f32_e32 vcc, v27, v28
	s_nop 1
	v_addc_co_u32_e32 v13, vcc, v13, v22, vcc
	v_cmp_gt_u32_e32 vcc, 3, v13
	s_nop 1
	v_cndmask_b32_e64 v13, 0, 64, vcc
	v_or_b32_e32 v25, v8, v13
	v_bitop3_b32 v180, v8, s5, v13 bitop3:0x32
	v_mov_b32_e32 v13, v170
	v_bitop3_b32 v193, v25, v24, s5 bitop3:0x54
	v_lshlrev_b32_e32 v8, 4, v13
	v_and_b32_e32 v8, 0xf0, v8
	v_add_u32_e32 v8, 0, v8
	v_lshrrev_b32_e32 v26, 4, v13
	v_and_b32_e32 v248, 0xf0, v13
	v_xor_b32_e32 v248, v248, v8
	v_mov_b32_e32 v249, 0
	v_mad_u64_u32 v[22:23], s[6:7], v26, s33, v[248:249]
	s_waitcnt vmcnt(3)
	ds_write_b128 v22, v[0:3]
	v_add_u32_e32 v0, 0x200, v13
	v_lshrrev_b32_e32 v2, 4, v0
	v_mad_u64_u32 v[0:1], s[6:7], v2, s33, v[248:249]
	s_waitcnt vmcnt(2)
	ds_write_b128 v0, v[4:7]
	v_mad_u64_u32 v[0:1], s[6:7], v26, s84, v[8:9]
	s_waitcnt vmcnt(1)
	ds_write_b128 v0, v[14:17] offset:34816
	v_mad_u64_u32 v[0:1], s[6:7], v2, s84, v[8:9]
	s_waitcnt vmcnt(0)
	ds_write_b128 v0, v[18:21] offset:34816
	v_lshlrev_b32_e32 v0, 8, v11
	v_and_b32_e32 v1, 48, v10
	v_lshlrev_b32_e32 v248, 4, v11
	v_xor_b32_e32 v1, v1, v248
	v_add3_u32 v192, 0, v0, v1
	v_lshrrev_b32_e32 v0, 2, v11
	v_or_b32_e32 v0, v191, v0
	v_lshlrev_b32_e32 v1, 3, v10
	v_mul_u32_u24_e32 v0, 0x120, v0
	v_and_b32_e32 v1, 24, v1
	v_add3_u32 v176, 0, v0, v1
	v_and_b32_e32 v1, 64, v184
	v_xor_b32_e32 v0, 16, v184
	v_add_u32_e32 v1, 64, v1
	v_cmp_lt_i32_e32 vcc, v0, v1
	v_mov_b32_e32 v8, v9
	v_mov_b32_e32 v10, v9
	v_cndmask_b32_e32 v0, v184, v0, vcc
	v_lshlrev_b32_e32 v175, 2, v0
	v_xor_b32_e32 v0, 32, v184
	v_cmp_lt_i32_e32 vcc, v0, v1
	v_mov_b32_e32 v11, v9
	v_mov_b64_e32 v[18:19], v[10:11]
	v_cndmask_b32_e32 v0, v184, v0, vcc
	v_lshlrev_b32_e32 v174, 2, v0
	v_mov_b64_e32 v[0:1], v[8:9]
	v_mov_b64_e32 v[26:27], v[10:11]
	v_mov_b64_e32 v[34:35], v[10:11]
	v_mov_b64_e32 v[14:15], v[10:11]
	v_mov_b64_e32 v[4:5], v[8:9]
	v_mov_b64_e32 v[22:23], v[10:11]
	v_mov_b64_e32 v[30:31], v[10:11]
	v_mov_b64_e32 v[38:39], v[10:11]
	v_mov_b64_e32 v[42:43], v[10:11]
	v_mov_b64_e32 v[46:47], v[10:11]
	v_mov_b64_e32 v[50:51], v[10:11]
	v_mov_b64_e32 v[54:55], v[10:11]
	v_mov_b64_e32 v[58:59], v[10:11]
	v_mov_b64_e32 v[62:63], v[10:11]
	v_mov_b64_e32 v[66:67], v[10:11]
	s_or_b32 s6, s17, 2
	v_mov_b64_e32 v[2:3], v[10:11]
	v_mov_b64_e32 v[16:17], v[8:9]
	v_mov_b64_e32 v[24:25], v[8:9]
	v_mov_b64_e32 v[32:33], v[8:9]
	v_mov_b64_e32 v[12:13], v[8:9]
	v_mov_b64_e32 v[6:7], v[10:11]
	v_mov_b64_e32 v[20:21], v[8:9]
	v_mov_b64_e32 v[28:29], v[8:9]
	v_mov_b64_e32 v[36:37], v[8:9]
	v_mov_b64_e32 v[40:41], v[8:9]
	v_mov_b64_e32 v[44:45], v[8:9]
	v_mov_b64_e32 v[48:49], v[8:9]
	v_mov_b64_e32 v[52:53], v[8:9]
	v_mov_b64_e32 v[56:57], v[8:9]
	v_mov_b64_e32 v[60:61], v[8:9]
	v_mov_b64_e32 v[64:65], v[8:9]
	v_mov_b32_e32 v11, 0xf149f2ca
	v_mov_b32_e32 v10, 0
	s_mov_b32 s7, 0
	s_waitcnt lgkmcnt(0)
	s_barrier
.LBB0_894:
	v_sub_co_u32_e64 v116, s[38:39], s7, 4
	s_xor_b64 s[4:5], s[38:39], -1
	s_add_i32 s44, s9, s85
	s_cmp_gt_u32 s7, 2
	s_cselect_b64 s[36:37], -1, 0
	s_add_i32 s45, s44, 64
	s_add_i32 s46, s85, 0xffffff40
	s_cmp_lt_u32 s7, 3
	s_cselect_b64 s[62:63], -1, 0
	s_and_b64 s[42:43], s[62:63], exec
	s_cselect_b32 s45, s45, s46
	v_lshrrev_b32_e32 v114, 4, v170
	v_and_b32_e32 v115, 15, v170
	v_mul_u32_u24_e32 v114, 0x3000, v114
	v_lshl_or_b32 v114, v115, 4, v114
	s_mul_i32 s42, s45, 0x3000
	v_add_u32_e32 v112, s42, v114
	s_add_i32 s43, s42, 0x60000
	v_add_u32_e32 v113, s43, v114
	global_load_dwordx4 v[100:103], v112, s[24:25]
	v_ashrrev_i32_e32 v8, 2, v116
	global_load_dwordx4 v[108:111], v113, s[24:25]
	global_load_dwordx4 v[104:107], v112, s[26:27]
	s_mov_b64 s[40:41], -1
	global_load_dwordx4 v[112:115], v113, s[26:27]
	v_lshlrev_b32_e64 v8, v8, 1
	s_and_b64 vcc, exec, s[4:5]
	s_cbranch_vccz .LBB0_897
	v_and_b32_e32 v116, v8, v193
	v_cmp_ne_u32_e32 vcc, 0, v116
	s_cmp_lg_u64 vcc, 0
	s_cselect_b64 s[42:43], -1, 0
	s_cbranch_execz .LBB0_898

.LBB0_899:
	s_add_i32 s40, s85, 0xffffff00
	s_and_b64 s[38:39], s[38:39], exec
	s_mul_i32 s38, s86, 0x4400
	v_add_u32_e32 v154, s38, v192
	v_xor_b32_e32 v223, 64, v154
	v_xor_b32_e32 v250, 0x80, v154
	v_xor_b32_e32 v251, 0xc0, v154
	ds_read_b128 v[116:119], v154
	ds_read_b128 v[120:123], v154 offset:4096
	ds_read_b128 v[124:127], v154 offset:8192
	ds_read_b128 v[128:131], v154 offset:12288
	ds_read_b128 v[194:197], v223
	ds_read_b128 v[198:201], v223 offset:4096
	ds_read_b128 v[202:205], v223 offset:8192
	ds_read_b128 v[206:209], v223 offset:12288
	ds_read_b128 v[226:229], v250
	ds_read_b128 v[230:233], v250 offset:4096
	ds_read_b128 v[234:237], v250 offset:8192
	ds_read_b128 v[238:241], v250 offset:12288
	ds_read_b128 v[242:245], v251
	ds_read_b128 v[246:249], v251 offset:4096
	s_cselect_b32 s40, s44, s40
	s_mov_b64 s[38:39], -1
	s_and_b64 vcc, exec, s[4:5]
	s_waitcnt lgkmcnt(13)
	v_mfma_f32_16x16x32_bf16 v[132:135], v[116:119], v[92:95], 0
	v_mfma_f32_16x16x32_bf16 v[116:119], v[116:119], v[96:99], 0
	s_waitcnt lgkmcnt(12)
	v_mfma_f32_16x16x32_bf16 v[136:139], v[120:123], v[92:95], 0
	v_mfma_f32_16x16x32_bf16 v[120:123], v[120:123], v[96:99], 0
	s_waitcnt lgkmcnt(11)
	v_mfma_f32_16x16x32_bf16 v[140:143], v[124:127], v[92:95], 0
	v_mfma_f32_16x16x32_bf16 v[124:127], v[124:127], v[96:99], 0
	s_waitcnt lgkmcnt(10)
	v_mfma_f32_16x16x32_bf16 v[144:147], v[128:131], v[92:95], 0
	v_mfma_f32_16x16x32_bf16 v[128:131], v[128:131], v[96:99], 0
	s_waitcnt lgkmcnt(9)
	v_mfma_f32_16x16x32_bf16 v[132:135], v[194:197], v[84:87], v[132:135]
	v_mfma_f32_16x16x32_bf16 v[116:119], v[194:197], v[88:91], v[116:119]
	ds_read_b128 v[194:197], v251 offset:8192
	s_waitcnt lgkmcnt(9)
	v_mfma_f32_16x16x32_bf16 v[136:139], v[198:201], v[84:87], v[136:139]
	v_mfma_f32_16x16x32_bf16 v[120:123], v[198:201], v[88:91], v[120:123]
	ds_read_b128 v[198:201], v251 offset:12288
	s_waitcnt lgkmcnt(9)
	v_mfma_f32_16x16x32_bf16 v[140:143], v[202:205], v[84:87], v[140:143]
	v_mfma_f32_16x16x32_bf16 v[124:127], v[202:205], v[88:91], v[124:127]
	s_waitcnt lgkmcnt(8)
	v_mfma_f32_16x16x32_bf16 v[144:147], v[206:209], v[84:87], v[144:147]
	v_mfma_f32_16x16x32_bf16 v[128:131], v[206:209], v[88:91], v[128:131]
	s_waitcnt lgkmcnt(7)
	v_mfma_f32_16x16x32_bf16 v[132:135], v[226:229], v[76:79], v[132:135]
	v_mfma_f32_16x16x32_bf16 v[116:119], v[226:229], v[80:83], v[116:119]
	s_waitcnt lgkmcnt(6)
	v_mfma_f32_16x16x32_bf16 v[136:139], v[230:233], v[76:79], v[136:139]
	v_mfma_f32_16x16x32_bf16 v[120:123], v[230:233], v[80:83], v[120:123]
	s_waitcnt lgkmcnt(5)
	v_mfma_f32_16x16x32_bf16 v[140:143], v[234:237], v[76:79], v[140:143]
	v_mfma_f32_16x16x32_bf16 v[124:127], v[234:237], v[80:83], v[124:127]
	s_waitcnt lgkmcnt(4)
	v_mfma_f32_16x16x32_bf16 v[144:147], v[238:241], v[76:79], v[144:147]
	v_mfma_f32_16x16x32_bf16 v[128:131], v[238:241], v[80:83], v[128:131]
	s_waitcnt lgkmcnt(3)
	v_mfma_f32_16x16x32_bf16 v[132:135], v[242:245], v[68:71], v[132:135]
	v_mfma_f32_16x16x32_bf16 v[116:119], v[242:245], v[72:75], v[116:119]
	s_waitcnt lgkmcnt(2)
	v_mfma_f32_16x16x32_bf16 v[136:139], v[246:249], v[68:71], v[136:139]
	v_mfma_f32_16x16x32_bf16 v[120:123], v[246:249], v[72:75], v[120:123]
	s_waitcnt lgkmcnt(1)
	v_mfma_f32_16x16x32_bf16 v[140:143], v[194:197], v[68:71], v[140:143]
	v_mfma_f32_16x16x32_bf16 v[124:127], v[194:197], v[72:75], v[124:127]
	s_waitcnt lgkmcnt(0)
	v_mfma_f32_16x16x32_bf16 v[144:147], v[198:201], v[68:71], v[144:147]
	v_mfma_f32_16x16x32_bf16 v[128:131], v[198:201], v[72:75], v[128:131]
	s_cbranch_vccz .LBB0_903
	v_and_b32_e32 v154, v8, v190
	v_cmp_eq_u32_e32 vcc, 0, v154
	v_mov_b32_e32 v195, v135
	v_mov_b32_e32 v200, v134
	v_mov_b32_e32 v204, v133
	v_mov_b32_e32 v208, v132
	v_mov_b32_e32 v196, v139
	v_mov_b32_e32 v199, v138
	v_mov_b32_e32 v203, v137
	v_mov_b32_e32 v207, v136
	v_mov_b32_e32 v194, v143
	v_mov_b32_e32 v197, v142
	v_mov_b32_e32 v202, v141
	v_mov_b32_e32 v206, v140
	v_mov_b32_e32 v198, v147
	v_mov_b32_e32 v201, v146
	v_mov_b32_e32 v205, v145
	v_mov_b32_e32 v209, v144
	s_and_saveexec_b64 s[38:39], vcc
	s_cbranch_execz .LBB0_902
	v_mov_b32_e32 v195, 0xff800000
	v_mov_b32_e32 v200, 0xff800000
	v_mov_b32_e32 v204, 0xff800000
	v_mov_b32_e32 v208, 0xff800000
	v_mov_b32_e32 v196, 0xff800000
	v_mov_b32_e32 v199, 0xff800000
	v_mov_b32_e32 v203, 0xff800000
	v_mov_b32_e32 v207, 0xff800000
	v_mov_b32_e32 v194, 0xff800000
	v_mov_b32_e32 v197, 0xff800000
	v_mov_b32_e32 v202, 0xff800000
	v_mov_b32_e32 v206, 0xff800000
	v_mov_b32_e32 v198, 0xff800000
	v_mov_b32_e32 v201, 0xff800000
	v_mov_b32_e32 v205, 0xff800000
	v_mov_b32_e32 v209, 0xff800000

.LBB0_905:
	v_max3_f32 v132, v195, v200, v204
	v_max3_f32 v133, v197, v202, v206
	v_max3_f32 v132, v132, v208, v196
	v_max3_f32 v133, v133, v198, v201
	v_max3_f32 v132, v132, v199, v203
	v_max3_f32 v133, v133, v205, v209
	v_max3_f32 v132, v132, v207, v194
	v_max3_f32 v132, v132, s3, v133
	ds_bpermute_b32 v133, v175, v132
	s_andn2_b64 vcc, exec, s[4:5]
	s_mov_b64 s[4:5], -1
	s_waitcnt lgkmcnt(0)
	v_max_f32_e32 v221, v132, v133
	ds_bpermute_b32 v222, v174, v221
	s_cbranch_vccnz .LBB0_909
	v_and_b32_e32 v8, v8, v180
	v_cmp_eq_u32_e32 vcc, 0, v8
	v_mov_b32_e32 v132, v119
	v_mov_b32_e32 v133, v118
	v_mov_b32_e32 v135, v117
	v_mov_b32_e32 v138, v116
	v_mov_b32_e32 v134, v123
	v_mov_b32_e32 v136, v122
	v_mov_b32_e32 v139, v121
	v_mov_b32_e32 v143, v120
	v_mov_b32_e32 v137, v127
	v_mov_b32_e32 v140, v126
	v_mov_b32_e32 v142, v125
	v_mov_b32_e32 v145, v124
	v_mov_b32_e32 v141, v131
	v_mov_b32_e32 v144, v130
	v_mov_b32_e32 v146, v129
	v_mov_b32_e32 v147, v128
	s_and_saveexec_b64 s[4:5], vcc
	s_cbranch_execz .LBB0_908
	v_mov_b32_e32 v132, 0xff800000
	v_mov_b32_e32 v133, 0xff800000
	v_mov_b32_e32 v135, 0xff800000
	v_mov_b32_e32 v138, 0xff800000
	v_mov_b32_e32 v134, 0xff800000
	v_mov_b32_e32 v136, 0xff800000
	v_mov_b32_e32 v139, 0xff800000
	v_mov_b32_e32 v143, 0xff800000
	v_mov_b32_e32 v137, 0xff800000
	v_mov_b32_e32 v140, 0xff800000
	v_mov_b32_e32 v142, 0xff800000
	v_mov_b32_e32 v145, 0xff800000
	v_mov_b32_e32 v141, 0xff800000
	v_mov_b32_e32 v144, 0xff800000
	v_mov_b32_e32 v146, 0xff800000
	v_mov_b32_e32 v147, 0xff800000

.LBB0_911:
	s_waitcnt lgkmcnt(0)
	v_max3_f32 v8, v11, v221, v222
	v_sub_f32_e32 v116, v208, v8
	v_exp_f32_e32 v116, v116
	v_sub_f32_e32 v117, v204, v8
	v_exp_f32_e32 v117, v117
	v_sub_f32_e32 v118, v200, v8
	v_exp_f32_e32 v118, v118
	v_sub_f32_e32 v119, v195, v8
	v_exp_f32_e32 v119, v119
	v_add_f32_e32 v120, 0, v116
	v_add_f32_e32 v120, v117, v120
	v_add_f32_e32 v120, v118, v120
	v_add_f32_e32 v122, v119, v120
	v_cvt_pk_bf16_f32 v120, v116, v117
	v_sub_f32_e32 v116, v207, v8
	v_exp_f32_e32 v116, v116
	v_sub_f32_e32 v117, v203, v8
	v_cvt_pk_bf16_f32 v121, v118, v119
	v_exp_f32_e32 v117, v117
	v_sub_f32_e32 v118, v199, v8
	v_exp_f32_e32 v118, v118
	v_sub_f32_e32 v119, v196, v8
	v_exp_f32_e32 v119, v119
	v_add_f32_e32 v122, v116, v122
	v_add_f32_e32 v122, v117, v122
	v_add_f32_e32 v122, v118, v122
	v_add_f32_e32 v124, v119, v122
	v_cvt_pk_bf16_f32 v122, v116, v117
	v_sub_f32_e32 v116, v206, v8
	v_exp_f32_e32 v116, v116
	v_sub_f32_e32 v117, v202, v8
	v_cvt_pk_bf16_f32 v123, v118, v119
	v_exp_f32_e32 v117, v117
	v_add_f32_e32 v118, v116, v124
	v_sub_f32_e32 v119, v197, v8
	v_sub_f32_e32 v124, v194, v8
	v_exp_f32_e32 v119, v119
	v_exp_f32_e32 v124, v124
	v_add_f32_e32 v118, v117, v118
	v_sub_f32_e32 v125, v209, v8
	v_add_f32_e32 v118, v119, v118
	v_exp_f32_e32 v125, v125
	v_cvt_pk_bf16_f32 v116, v116, v117
	v_cvt_pk_bf16_f32 v117, v119, v124
	v_sub_f32_e32 v119, v205, v8
	v_add_f32_e32 v118, v124, v118
	v_exp_f32_e32 v119, v119
	v_sub_f32_e32 v124, v201, v8
	v_exp_f32_e32 v126, v124
	v_sub_f32_e32 v124, v198, v8
	v_sub_f32_e32 v11, v11, v8
	v_exp_f32_e32 v127, v124
	v_add_f32_e32 v118, v125, v118
	v_exp_f32_e32 v124, v11
	v_add_f32_e32 v118, v119, v118
	v_add_f32_e32 v118, v126, v118
	v_add_f32_e32 v154, v127, v118
	v_fmac_f32_e32 v154, v10, v124
	v_cvt_pk_bf16_f32 v118, v125, v119
	v_pk_mul_f32 v[66:67], v[66:67], v[124:125] op_sel_hi:[1,0]
	v_pk_mul_f32 v[64:65], v[64:65], v[124:125] op_sel_hi:[1,0]
	v_pk_mul_f32 v[62:63], v[62:63], v[124:125] op_sel_hi:[1,0]
	v_pk_mul_f32 v[60:61], v[60:61], v[124:125] op_sel_hi:[1,0]
	v_pk_mul_f32 v[58:59], v[58:59], v[124:125] op_sel_hi:[1,0]
	v_pk_mul_f32 v[56:57], v[56:57], v[124:125] op_sel_hi:[1,0]
	v_pk_mul_f32 v[54:55], v[54:55], v[124:125] op_sel_hi:[1,0]
	v_pk_mul_f32 v[52:53], v[52:53], v[124:125] op_sel_hi:[1,0]
	v_max3_f32 v10, v132, v133, v135
	v_cvt_pk_bf16_f32 v119, v126, v127
	v_max3_f32 v11, v140, v142, v145
	v_max3_f32 v10, v10, v138, v134
	v_max3_f32 v11, v11, v141, v144
	v_max3_f32 v10, v10, v136, v139
	v_max3_f32 v11, v11, v146, v147
	v_max3_f32 v10, v10, v143, v137
	v_max3_f32 v10, v10, s3, v11
	ds_bpermute_b32 v11, v175, v10
	v_pk_mul_f32 v[50:51], v[50:51], v[124:125] op_sel_hi:[1,0]
	v_pk_mul_f32 v[48:49], v[48:49], v[124:125] op_sel_hi:[1,0]
	v_pk_mul_f32 v[46:47], v[46:47], v[124:125] op_sel_hi:[1,0]
	v_pk_mul_f32 v[44:45], v[44:45], v[124:125] op_sel_hi:[1,0]
	s_waitcnt lgkmcnt(0)
	v_max_f32_e32 v10, v10, v11
	ds_bpermute_b32 v11, v174, v10
	v_pk_mul_f32 v[42:43], v[42:43], v[124:125] op_sel_hi:[1,0]
	v_pk_mul_f32 v[40:41], v[40:41], v[124:125] op_sel_hi:[1,0]
	v_pk_mul_f32 v[38:39], v[38:39], v[124:125] op_sel_hi:[1,0]
	v_pk_mul_f32 v[36:37], v[36:37], v[124:125] op_sel_hi:[1,0]
	s_waitcnt lgkmcnt(0)
	v_max3_f32 v155, v181, v10, v11
	v_sub_f32_e32 v11, v138, v155
	v_exp_f32_e32 v11, v11
	v_sub_f32_e32 v124, v135, v155
	v_exp_f32_e32 v124, v124
	v_sub_f32_e32 v125, v133, v155
	v_exp_f32_e32 v125, v125
	v_sub_f32_e32 v126, v132, v155
	v_exp_f32_e32 v126, v126
	v_add_f32_e32 v127, 0, v11
	v_add_f32_e32 v127, v124, v127
	v_cvt_pk_bf16_f32 v128, v11, v124
	v_sub_f32_e32 v11, v143, v155
	v_sub_f32_e32 v124, v139, v155
	v_add_f32_e32 v127, v125, v127
	v_exp_f32_e32 v11, v11
	v_exp_f32_e32 v124, v124
	v_add_f32_e32 v127, v126, v127
	v_cvt_pk_bf16_f32 v129, v125, v126
	v_sub_f32_e32 v125, v136, v155
	v_sub_f32_e32 v126, v134, v155
	v_exp_f32_e32 v125, v125
	v_exp_f32_e32 v126, v126
	v_add_f32_e32 v127, v11, v127
	v_cvt_pk_bf16_f32 v130, v11, v124
	v_sub_f32_e32 v11, v145, v155
	v_add_f32_e32 v127, v124, v127
	v_exp_f32_e32 v11, v11
	v_sub_f32_e32 v124, v142, v155
	v_add_f32_e32 v127, v125, v127
	v_cvt_pk_bf16_f32 v131, v125, v126
	v_exp_f32_e32 v124, v124
	v_sub_f32_e32 v125, v140, v155
	v_add_f32_e32 v127, v126, v127
	v_exp_f32_e32 v125, v125
	v_sub_f32_e32 v126, v137, v155
	v_exp_f32_e32 v126, v126
	v_add_f32_e32 v127, v11, v127
	v_add_f32_e32 v127, v124, v127
	v_add_f32_e32 v127, v125, v127
	v_cvt_pk_bf16_f32 v124, v11, v124
	v_sub_f32_e32 v11, v147, v155
	v_add_f32_e32 v127, v126, v127
	v_cvt_pk_bf16_f32 v125, v125, v126
	v_exp_f32_e32 v11, v11
	v_sub_f32_e32 v126, v146, v155
	v_exp_f32_e32 v126, v126
	v_sub_f32_e32 v132, v144, v155
	v_exp_f32_e32 v132, v132
	v_sub_f32_e32 v133, v141, v155
	v_exp_f32_e32 v133, v133
	v_add_f32_e32 v127, v11, v127
	v_add_f32_e32 v127, v126, v127
	s_mul_i32 s4, s86, 0x4800
	v_sub_f32_e32 v10, v181, v155
	v_add_f32_e32 v127, v132, v127
	v_add_u32_e32 v157, s4, v176
	v_add_f32_e32 v156, v133, v127
	v_cvt_pk_bf16_f32 v127, v132, v133
	v_exp_f32_e32 v10, v10
	ds_read_b64_tr_b16 v[134:135], v157 offset:39424
	ds_read_b64_tr_b16 v[132:133], v157 offset:34816
	ds_read_b64_tr_b16 v[136:137], v157 offset:34848
	ds_read_b64_tr_b16 v[140:141], v157 offset:34880
	ds_read_b64_tr_b16 v[144:145], v157 offset:34912
	ds_read_b64_tr_b16 v[138:139], v157 offset:39456
	ds_read_b64_tr_b16 v[142:143], v157 offset:39488
	ds_read_b64_tr_b16 v[146:147], v157 offset:39520
	s_waitcnt lgkmcnt(6)
	v_mfma_f32_16x16x32_bf16 v[64:67], v[132:135], v[120:123], v[64:67]
	v_mul_f32_e64 v30, v30, v10
	v_mul_f32_e64 v31, v31, v10
	v_pk_mul_f32 v[28:29], v[28:29], v[10:11] op_sel_hi:[1,0]
	v_pk_mul_f32 v[22:23], v[22:23], v[10:11] op_sel_hi:[1,0]
	v_pk_mul_f32 v[20:21], v[20:21], v[10:11] op_sel_hi:[1,0]
	v_pk_mul_f32 v[6:7], v[6:7], v[10:11] op_sel_hi:[1,0]
	v_pk_mul_f32 v[4:5], v[4:5], v[10:11] op_sel_hi:[1,0]
	v_mfma_f32_16x16x32_bf16 v[28:31], v[132:135], v[128:131], v[28:31]
	v_mul_f32_e64 v14, v14, v10
	v_mul_f32_e64 v15, v15, v10
	v_pk_mul_f32 v[12:13], v[12:13], v[10:11] op_sel_hi:[1,0]
	v_cvt_pk_bf16_f32 v126, v11, v126
	s_waitcnt lgkmcnt(2)
	v_mfma_f32_16x16x32_bf16 v[60:63], v[136:139], v[120:123], v[60:63]
	v_fmac_f32_e32 v156, v177, v10
	v_pk_mul_f32 v[34:35], v[34:35], v[10:11] op_sel_hi:[1,0]
	v_pk_mul_f32 v[32:33], v[32:33], v[10:11] op_sel_hi:[1,0]
	v_mfma_f32_16x16x32_bf16 v[20:23], v[136:139], v[128:131], v[20:23]
	v_mul_f32_e64 v26, v26, v10
	v_mul_f32_e64 v27, v27, v10
	v_pk_mul_f32 v[24:25], v[24:25], v[10:11] op_sel_hi:[1,0]
	v_pk_mul_f32 v[18:19], v[18:19], v[10:11] op_sel_hi:[1,0]
	s_waitcnt lgkmcnt(1)
	v_mfma_f32_16x16x32_bf16 v[56:59], v[140:143], v[120:123], v[56:59]
	v_mul_f32_e64 v16, v16, v10
	v_mul_f32_e64 v17, v17, v10
	v_pk_mul_f32 v[2:3], v[2:3], v[10:11] op_sel_hi:[1,0]
	v_pk_mul_f32 v[0:1], v[0:1], v[10:11] op_sel_hi:[1,0]
	v_mfma_f32_16x16x32_bf16 v[4:7], v[140:143], v[128:131], v[4:7]
	ds_read_b64_tr_b16 v[132:133], v157 offset:34944
	ds_read_b64_tr_b16 v[136:137], v157 offset:34976
	ds_read_b64_tr_b16 v[140:141], v157 offset:35008
	ds_read_b64_tr_b16 v[194:195], v157 offset:35040
	ds_read_b64_tr_b16 v[134:135], v157 offset:39552
	ds_read_b64_tr_b16 v[138:139], v157 offset:39584
	ds_read_b64_tr_b16 v[142:143], v157 offset:39616
	ds_read_b64_tr_b16 v[196:197], v157 offset:39648
	s_waitcnt lgkmcnt(8)
	v_mfma_f32_16x16x32_bf16 v[52:55], v[144:147], v[120:123], v[52:55]
	v_mfma_f32_16x16x32_bf16 v[10:13], v[144:147], v[128:131], v[12:15]
	s_waitcnt lgkmcnt(3)
	v_mfma_f32_16x16x32_bf16 v[48:51], v[132:135], v[120:123], v[48:51]
	v_mfma_f32_16x16x32_bf16 v[32:35], v[132:135], v[128:131], v[32:35]
	s_waitcnt lgkmcnt(2)
	v_mfma_f32_16x16x32_bf16 v[44:47], v[136:139], v[120:123], v[44:47]
	v_mfma_f32_16x16x32_bf16 v[24:27], v[136:139], v[128:131], v[24:27]
	s_waitcnt lgkmcnt(1)
	v_mfma_f32_16x16x32_bf16 v[40:43], v[140:143], v[120:123], v[40:43]
	v_mfma_f32_16x16x32_bf16 v[16:19], v[140:143], v[128:131], v[16:19]
	ds_read_b64_tr_b16 v[132:133], v157 offset:44032
	ds_read_b64_tr_b16 v[136:137], v157 offset:44064
	ds_read_b64_tr_b16 v[140:141], v157 offset:44096
	ds_read_b64_tr_b16 v[144:145], v157 offset:44128
	ds_read_b64_tr_b16 v[134:135], v157 offset:48640
	ds_read_b64_tr_b16 v[138:139], v157 offset:48672
	ds_read_b64_tr_b16 v[142:143], v157 offset:48704
	ds_read_b64_tr_b16 v[146:147], v157 offset:48736
	s_waitcnt lgkmcnt(8)
	v_mfma_f32_16x16x32_bf16 v[36:39], v[194:197], v[120:123], v[36:39]
	v_mfma_f32_16x16x32_bf16 v[0:3], v[194:197], v[128:131], v[0:3]
	s_waitcnt lgkmcnt(3)
	v_mfma_f32_16x16x32_bf16 v[64:67], v[132:135], v[116:119], v[64:67]
	v_mfma_f32_16x16x32_bf16 v[28:31], v[132:135], v[124:127], v[28:31]
	s_waitcnt lgkmcnt(2)
	v_mfma_f32_16x16x32_bf16 v[60:63], v[136:139], v[116:119], v[60:63]
	v_mfma_f32_16x16x32_bf16 v[20:23], v[136:139], v[124:127], v[20:23]
	ds_read_b64_tr_b16 v[120:121], v157 offset:44160
	ds_read_b64_tr_b16 v[128:129], v157 offset:44192
	ds_read_b64_tr_b16 v[132:133], v157 offset:44224
	ds_read_b64_tr_b16 v[136:137], v157 offset:44256
	ds_read_b64_tr_b16 v[122:123], v157 offset:48768
	ds_read_b64_tr_b16 v[130:131], v157 offset:48800
	ds_read_b64_tr_b16 v[134:135], v157 offset:48832
	ds_read_b64_tr_b16 v[138:139], v157 offset:48864
	s_waitcnt lgkmcnt(9)
	v_mfma_f32_16x16x32_bf16 v[56:59], v[140:143], v[116:119], v[56:59]
	v_mfma_f32_16x16x32_bf16 v[4:7], v[140:143], v[124:127], v[4:7]
	s_waitcnt lgkmcnt(8)
	v_mfma_f32_16x16x32_bf16 v[52:55], v[144:147], v[116:119], v[52:55]
	v_mfma_f32_16x16x32_bf16 v[12:15], v[144:147], v[124:127], v[10:13]
	s_waitcnt lgkmcnt(3)
	v_mfma_f32_16x16x32_bf16 v[48:51], v[120:123], v[116:119], v[48:51]
	v_mfma_f32_16x16x32_bf16 v[32:35], v[120:123], v[124:127], v[32:35]
	s_waitcnt lgkmcnt(2)
	v_mfma_f32_16x16x32_bf16 v[44:47], v[128:131], v[116:119], v[44:47]
	v_mfma_f32_16x16x32_bf16 v[24:27], v[128:131], v[124:127], v[24:27]
	s_waitcnt lgkmcnt(1)
	v_mfma_f32_16x16x32_bf16 v[40:43], v[132:135], v[116:119], v[40:43]
	v_mfma_f32_16x16x32_bf16 v[16:19], v[132:135], v[124:127], v[16:19]
	s_waitcnt lgkmcnt(0)
	v_mfma_f32_16x16x32_bf16 v[36:39], v[136:139], v[116:119], v[36:39]
	v_mfma_f32_16x16x32_bf16 v[0:3], v[136:139], v[124:127], v[0:3]
	v_mov_b32_e32 v10, v154
	v_mov_b32_e32 v177, v156
	v_mov_b32_e32 v11, v8
	v_mov_b32_e32 v181, v155
.LBB0_912:
	s_lshl_b32 s4, s86, 6
	s_xor_b32 s38, s4, 64
	s_mul_i32 s39, s38, 0x110
	v_lshrrev_b32_e32 v120, 4, v170
	v_and_b32_e32 v119, 15, v170
	v_and_b32_e32 v8, 15, v120
	v_xor_b32_e32 v8, v119, v8
	v_lshlrev_b32_e32 v8, 4, v8
	v_lshl_or_b32 v8, v120, 8, v8
	v_add_u32_e32 v8, s39, v8
	s_mul_i32 s4, s38, 0x120
	v_mul_u32_u24_e32 v116, 0x120, v120
	v_lshl_add_u32 v116, v119, 4, v116
	v_add_u32_e32 v116, s4, v116
	s_add_i32 s40, s7, 1
	s_add_i32 s85, s85, 64
	s_cmp_eq_u32 s7, s6
	s_waitcnt vmcnt(3)
	ds_write_b128 v8, v[100:103]
	s_waitcnt vmcnt(2)
	ds_write_b128 v8, v[108:111] offset:8192
	s_waitcnt vmcnt(1)
	ds_write_b128 v116, v[104:107] offset:34816
	s_waitcnt vmcnt(0)
	ds_write_b128 v116, v[112:115] offset:44032
	s_waitcnt lgkmcnt(0)
	s_barrier
	s_cbranch_scc1 .LBB0_914
	s_mov_b32 s7, s40
	s_branch .LBB0_894

.LBB0_919:
	s_and_b32 s6, s40, 1
	s_or_b32 s16, s85, s9
	s_add_i32 s17, s85, 0xffffff00
	s_and_b64 s[4:5], s[62:63], exec
	s_mul_i32 s4, s6, 0x4400
	v_add_u32_e32 v8, s4, v192
	v_xor_b32_e32 v223, 64, v8
	v_xor_b32_e32 v250, 0x80, v8
	v_xor_b32_e32 v251, 0xc0, v8
	ds_read_b128 v[100:103], v8
	ds_read_b128 v[108:111], v8 offset:4096
	ds_read_b128 v[116:119], v8 offset:8192
	ds_read_b128 v[124:127], v8 offset:12288
	s_cselect_b32 s16, s16, s17
	s_mov_b64 s[4:5], -1
	s_and_b64 vcc, exec, s[38:39]
	s_waitcnt lgkmcnt(3)
	v_mfma_f32_16x16x32_bf16 v[104:107], v[100:103], v[92:95], 0
	v_mfma_f32_16x16x32_bf16 v[100:103], v[100:103], v[96:99], 0
	s_waitcnt lgkmcnt(2)
	v_mfma_f32_16x16x32_bf16 v[112:115], v[108:111], v[92:95], 0
	v_mfma_f32_16x16x32_bf16 v[108:111], v[108:111], v[96:99], 0
	s_waitcnt lgkmcnt(1)
	v_mfma_f32_16x16x32_bf16 v[120:123], v[116:119], v[92:95], 0
	v_mfma_f32_16x16x32_bf16 v[116:119], v[116:119], v[96:99], 0
	s_waitcnt lgkmcnt(0)
	v_mfma_f32_16x16x32_bf16 v[92:95], v[124:127], v[92:95], 0
	v_mfma_f32_16x16x32_bf16 v[96:99], v[124:127], v[96:99], 0
	ds_read_b128 v[124:127], v223
	s_waitcnt lgkmcnt(0)
	v_mfma_f32_16x16x32_bf16 v[104:107], v[124:127], v[84:87], v[104:107]
	v_mfma_f32_16x16x32_bf16 v[100:103], v[124:127], v[88:91], v[100:103]
	ds_read_b128 v[124:127], v223 offset:4096
	s_waitcnt lgkmcnt(0)
	v_mfma_f32_16x16x32_bf16 v[112:115], v[124:127], v[84:87], v[112:115]
	v_mfma_f32_16x16x32_bf16 v[108:111], v[124:127], v[88:91], v[108:111]
	ds_read_b128 v[124:127], v223 offset:8192
	s_waitcnt lgkmcnt(0)
	v_mfma_f32_16x16x32_bf16 v[120:123], v[124:127], v[84:87], v[120:123]
	v_mfma_f32_16x16x32_bf16 v[116:119], v[124:127], v[88:91], v[116:119]
	ds_read_b128 v[124:127], v223 offset:12288
	s_waitcnt lgkmcnt(0)
	v_mfma_f32_16x16x32_bf16 v[84:87], v[124:127], v[84:87], v[92:95]
	s_nop 2
	ds_read_b128 v[92:95], v250
	v_mfma_f32_16x16x32_bf16 v[88:91], v[124:127], v[88:91], v[96:99]
	s_waitcnt lgkmcnt(0)
	v_mfma_f32_16x16x32_bf16 v[96:99], v[92:95], v[76:79], v[104:107]
	v_mfma_f32_16x16x32_bf16 v[92:95], v[92:95], v[80:83], v[100:103]
	s_nop 2
	ds_read_b128 v[100:103], v250 offset:4096
	s_waitcnt lgkmcnt(0)
	v_mfma_f32_16x16x32_bf16 v[104:107], v[100:103], v[76:79], v[112:115]
	v_mfma_f32_16x16x32_bf16 v[100:103], v[100:103], v[80:83], v[108:111]
	s_nop 2
	ds_read_b128 v[108:111], v250 offset:8192
	s_waitcnt lgkmcnt(0)
	v_mfma_f32_16x16x32_bf16 v[112:115], v[108:111], v[76:79], v[120:123]
	v_mfma_f32_16x16x32_bf16 v[108:111], v[108:111], v[80:83], v[116:119]
	s_nop 2
	ds_read_b128 v[116:119], v250 offset:12288
	s_waitcnt lgkmcnt(0)
	v_mfma_f32_16x16x32_bf16 v[120:123], v[116:119], v[76:79], v[84:87]
	ds_read_b128 v[76:79], v251
	s_nop 1
	ds_read_b128 v[84:87], v251 offset:8192
	v_mfma_f32_16x16x32_bf16 v[116:119], v[116:119], v[80:83], v[88:91]
	ds_read_b128 v[80:83], v251 offset:4096
	s_waitcnt lgkmcnt(2)
	v_mfma_f32_16x16x32_bf16 v[88:91], v[76:79], v[68:71], v[96:99]
	v_mfma_f32_16x16x32_bf16 v[76:79], v[76:79], v[72:75], v[92:95]
	s_waitcnt lgkmcnt(0)
	v_mfma_f32_16x16x32_bf16 v[92:95], v[80:83], v[68:71], v[104:107]
	s_nop 2
	ds_read_b128 v[104:107], v251 offset:12288
	v_mfma_f32_16x16x32_bf16 v[80:83], v[80:83], v[72:75], v[100:103]
	v_mfma_f32_16x16x32_bf16 v[96:99], v[84:87], v[68:71], v[112:115]
	v_mfma_f32_16x16x32_bf16 v[84:87], v[84:87], v[72:75], v[108:111]
	s_waitcnt lgkmcnt(0)
	v_mfma_f32_16x16x32_bf16 v[100:103], v[104:107], v[68:71], v[120:123]
	v_mfma_f32_16x16x32_bf16 v[68:71], v[104:107], v[72:75], v[116:119]
	s_cbranch_vccnz .LBB0_923
	v_and_b32_e32 v8, s7, v190
	v_cmp_eq_u32_e32 vcc, 0, v8
	v_mov_b32_e32 v72, v91
	v_mov_b32_e32 v73, v90
	v_mov_b32_e32 v109, v89
	v_mov_b32_e32 v113, v88
	v_mov_b32_e32 v74, v95
	v_mov_b32_e32 v75, v94
	v_mov_b32_e32 v108, v93
	v_mov_b32_e32 v112, v92
	v_mov_b32_e32 v8, v99
	v_mov_b32_e32 v104, v98
	v_mov_b32_e32 v107, v97
	v_mov_b32_e32 v111, v96
	v_mov_b32_e32 v105, v103
	v_mov_b32_e32 v106, v102
	v_mov_b32_e32 v110, v101
	v_mov_b32_e32 v114, v100
	s_and_saveexec_b64 s[4:5], vcc
	s_cbranch_execz .LBB0_922
	v_mov_b32_e32 v72, 0xff800000
	v_mov_b32_e32 v73, 0xff800000
	v_mov_b32_e32 v109, 0xff800000
	v_mov_b32_e32 v113, 0xff800000
	v_mov_b32_e32 v74, 0xff800000
	v_mov_b32_e32 v75, 0xff800000
	v_mov_b32_e32 v108, 0xff800000
	v_mov_b32_e32 v112, 0xff800000
	v_mov_b32_e32 v8, 0xff800000
	v_mov_b32_e32 v104, 0xff800000
	v_mov_b32_e32 v107, 0xff800000
	v_mov_b32_e32 v111, 0xff800000
	v_mov_b32_e32 v105, 0xff800000
	v_mov_b32_e32 v106, 0xff800000
	v_mov_b32_e32 v110, 0xff800000
	v_mov_b32_e32 v114, 0xff800000
